# lane exchanges with xor 1/2/4/8 partners in P2 / attention / retention epilogues and row sums: DPP moves instead of ds_bpermute round trips
# speedup vs baseline: 1.0057x; 1.0027x over previous
; __device__ __forceinline__ int crow(int r, int hi) { return (r & 3) + 8 * (r >> 2) + 4 * hi; }
; __device__ __forceinline__ unsigned cvtpk(float lo, float hi) { unsigned r; asm volatile("v_cvt_pk_bf16_f32 %0, %1, %2" : "=v"(r) : "v"(lo), "v"(hi)); return r; }
; __device__ __forceinline__ void ret_state_scan(const bf16_t* __restrict__ proj, bf16_t* __restrict__ state, int b, int h, int d4, int e2, char* lds) {
;     ...
;             bf16_t* dst = Sp + (size_t)(st >> 1) * 65536;
; #pragma unroll
;             for (int r = 0; r < 16; ++r) { const float v = R[r]; const float vn = __shfl_xor(v, 1);
;                 if ((r32 & 1) == 0) *(unsigned*)(dst + (size_t)crow(r, hi) * 256 + r32) = cvtpk(v, vn); } }
.LBB0_216:
	v_and_b32_e32 v24, 64, v27
	v_xor_b32_e32 v16, 1, v27
	v_add_u32_e32 v24, 64, v24
	v_cmp_lt_i32_e32 vcc, v16, v24
	v_lshl_add_u64 v[24:25], s[76:77], 0, v[22:23]
	s_nop 0
	v_cndmask_b32_e32 v16, v27, v16, vcc
	v_lshlrev_b32_e32 v16, 2, v16
	s_nop 1
	v_mov_b32_dpp v29, v0 quad_perm:[1,0,3,2] row_mask:0xf bank_mask:0xf
	s_and_saveexec_b64 s[24:25], s[0:1]
	s_cbranch_execz .LBB0_218
	v_add_co_u32_e32 v30, vcc, 0x6810000, v24
	s_waitcnt lgkmcnt(0)
	v_cvt_pk_bf16_f32 v29, v0, v29
	s_nop 0
	v_addc_co_u32_e32 v31, vcc, 0, v25, vcc
	global_store_dword v[30:31], v29, off
.LBB0_218:
	s_or_b64 exec, exec, s[24:25]
	s_waitcnt lgkmcnt(0)
	s_nop 1
	v_mov_b32_dpp v29, v1 quad_perm:[1,0,3,2] row_mask:0xf bank_mask:0xf
	s_and_saveexec_b64 s[24:25], s[0:1]
	s_cbranch_execz .LBB0_220
	v_add_co_u32_e32 v30, vcc, 0x6810000, v24
	s_waitcnt lgkmcnt(0)
	v_cvt_pk_bf16_f32 v29, v1, v29
	s_nop 0
	v_addc_co_u32_e32 v31, vcc, 0, v25, vcc
	global_store_dword v[30:31], v29, off offset:512
.LBB0_220:
	s_or_b64 exec, exec, s[24:25]
	s_waitcnt lgkmcnt(0)
	s_nop 1
	v_mov_b32_dpp v29, v2 quad_perm:[1,0,3,2] row_mask:0xf bank_mask:0xf
	s_and_saveexec_b64 s[24:25], s[0:1]
	s_cbranch_execz .LBB0_222
	v_add_co_u32_e32 v30, vcc, 0x6810000, v24
	s_waitcnt lgkmcnt(0)
	v_cvt_pk_bf16_f32 v29, v2, v29
	s_nop 0
	v_addc_co_u32_e32 v31, vcc, 0, v25, vcc
	global_store_dword v[30:31], v29, off offset:1024
.LBB0_222:
	s_or_b64 exec, exec, s[24:25]
	s_waitcnt lgkmcnt(0)
	s_nop 1
	v_mov_b32_dpp v29, v3 quad_perm:[1,0,3,2] row_mask:0xf bank_mask:0xf
	s_and_saveexec_b64 s[24:25], s[0:1]
	s_cbranch_execz .LBB0_224
	v_add_co_u32_e32 v30, vcc, 0x6810000, v24
	s_waitcnt lgkmcnt(0)
	v_cvt_pk_bf16_f32 v29, v3, v29
	s_nop 0
	v_addc_co_u32_e32 v31, vcc, 0, v25, vcc
	global_store_dword v[30:31], v29, off offset:1536
.LBB0_224:
	s_or_b64 exec, exec, s[24:25]
	s_waitcnt lgkmcnt(0)
	s_nop 1
	v_mov_b32_dpp v29, v4 quad_perm:[1,0,3,2] row_mask:0xf bank_mask:0xf
	s_and_saveexec_b64 s[24:25], s[0:1]
	s_cbranch_execz .LBB0_226
	v_add_co_u32_e32 v30, vcc, 0x6811000, v24
	s_waitcnt lgkmcnt(0)
	v_cvt_pk_bf16_f32 v29, v4, v29
	s_nop 0
	v_addc_co_u32_e32 v31, vcc, 0, v25, vcc
	global_store_dword v[30:31], v29, off
.LBB0_226:
	s_or_b64 exec, exec, s[24:25]
	s_waitcnt lgkmcnt(0)
	s_nop 1
	v_mov_b32_dpp v29, v5 quad_perm:[1,0,3,2] row_mask:0xf bank_mask:0xf
	s_and_saveexec_b64 s[24:25], s[0:1]
	s_cbranch_execz .LBB0_228
	v_add_co_u32_e32 v30, vcc, 0x6811000, v24
	s_waitcnt lgkmcnt(0)
	v_cvt_pk_bf16_f32 v29, v5, v29
	s_nop 0
	v_addc_co_u32_e32 v31, vcc, 0, v25, vcc
	global_store_dword v[30:31], v29, off offset:512
.LBB0_228:
	s_or_b64 exec, exec, s[24:25]
	s_waitcnt lgkmcnt(0)
	s_nop 1
	v_mov_b32_dpp v29, v6 quad_perm:[1,0,3,2] row_mask:0xf bank_mask:0xf
	s_and_saveexec_b64 s[24:25], s[0:1]
	s_cbranch_execz .LBB0_230
	v_add_co_u32_e32 v30, vcc, 0x6811000, v24
	s_waitcnt lgkmcnt(0)
	v_cvt_pk_bf16_f32 v29, v6, v29
	s_nop 0
	v_addc_co_u32_e32 v31, vcc, 0, v25, vcc
	global_store_dword v[30:31], v29, off offset:1024
.LBB0_230:
	s_or_b64 exec, exec, s[24:25]
	s_waitcnt lgkmcnt(0)
	s_nop 1
	v_mov_b32_dpp v29, v7 quad_perm:[1,0,3,2] row_mask:0xf bank_mask:0xf
	s_and_saveexec_b64 s[24:25], s[0:1]
	s_cbranch_execz .LBB0_232
	v_add_co_u32_e32 v30, vcc, 0x6811000, v24
	s_waitcnt lgkmcnt(0)
	v_cvt_pk_bf16_f32 v29, v7, v29
	s_nop 0
	v_addc_co_u32_e32 v31, vcc, 0, v25, vcc
	global_store_dword v[30:31], v29, off offset:1536
.LBB0_232:
	s_or_b64 exec, exec, s[24:25]
	s_waitcnt lgkmcnt(0)
	s_nop 1
	v_mov_b32_dpp v29, v8 quad_perm:[1,0,3,2] row_mask:0xf bank_mask:0xf
	s_and_saveexec_b64 s[24:25], s[0:1]
	s_cbranch_execz .LBB0_234
	v_add_co_u32_e32 v30, vcc, 0x6812000, v24
	s_waitcnt lgkmcnt(0)
	v_cvt_pk_bf16_f32 v29, v8, v29
	s_nop 0
	v_addc_co_u32_e32 v31, vcc, 0, v25, vcc
	global_store_dword v[30:31], v29, off
.LBB0_234:
	s_or_b64 exec, exec, s[24:25]
	s_waitcnt lgkmcnt(0)
	s_nop 1
	v_mov_b32_dpp v29, v9 quad_perm:[1,0,3,2] row_mask:0xf bank_mask:0xf
	s_and_saveexec_b64 s[24:25], s[0:1]
	s_cbranch_execz .LBB0_236
	v_add_co_u32_e32 v30, vcc, 0x6812000, v24
	s_waitcnt lgkmcnt(0)
	v_cvt_pk_bf16_f32 v29, v9, v29
	s_nop 0
	v_addc_co_u32_e32 v31, vcc, 0, v25, vcc
	global_store_dword v[30:31], v29, off offset:512
.LBB0_236:
	s_or_b64 exec, exec, s[24:25]
	s_waitcnt lgkmcnt(0)
	s_nop 1
	v_mov_b32_dpp v29, v10 quad_perm:[1,0,3,2] row_mask:0xf bank_mask:0xf
	s_and_saveexec_b64 s[24:25], s[0:1]
	s_cbranch_execz .LBB0_238
	v_add_co_u32_e32 v30, vcc, 0x6812000, v24
	s_waitcnt lgkmcnt(0)
	v_cvt_pk_bf16_f32 v29, v10, v29
	s_nop 0
	v_addc_co_u32_e32 v31, vcc, 0, v25, vcc
	global_store_dword v[30:31], v29, off offset:1024
.LBB0_238:
	s_or_b64 exec, exec, s[24:25]
	s_waitcnt lgkmcnt(0)
	s_nop 1
	v_mov_b32_dpp v29, v11 quad_perm:[1,0,3,2] row_mask:0xf bank_mask:0xf
	s_and_saveexec_b64 s[24:25], s[0:1]
	s_cbranch_execz .LBB0_240
	v_add_co_u32_e32 v30, vcc, 0x6812000, v24
	s_waitcnt lgkmcnt(0)
	v_cvt_pk_bf16_f32 v29, v11, v29
	s_nop 0
	v_addc_co_u32_e32 v31, vcc, 0, v25, vcc
	global_store_dword v[30:31], v29, off offset:1536
.LBB0_240:
	s_or_b64 exec, exec, s[24:25]
	s_waitcnt lgkmcnt(0)
	s_nop 1
	v_mov_b32_dpp v29, v12 quad_perm:[1,0,3,2] row_mask:0xf bank_mask:0xf
	s_and_saveexec_b64 s[24:25], s[0:1]
	s_cbranch_execz .LBB0_242
	v_add_co_u32_e32 v30, vcc, 0x6813000, v24
	s_waitcnt lgkmcnt(0)
	v_cvt_pk_bf16_f32 v29, v12, v29
	s_nop 0
	v_addc_co_u32_e32 v31, vcc, 0, v25, vcc
	global_store_dword v[30:31], v29, off
.LBB0_242:
	s_or_b64 exec, exec, s[24:25]
	s_waitcnt lgkmcnt(0)
	s_nop 1
	v_mov_b32_dpp v29, v13 quad_perm:[1,0,3,2] row_mask:0xf bank_mask:0xf
	s_and_saveexec_b64 s[24:25], s[0:1]
	s_cbranch_execz .LBB0_244
	v_add_co_u32_e32 v30, vcc, 0x6813000, v24
	s_waitcnt lgkmcnt(0)
	v_cvt_pk_bf16_f32 v29, v13, v29
	s_nop 0
	v_addc_co_u32_e32 v31, vcc, 0, v25, vcc
	global_store_dword v[30:31], v29, off offset:512
.LBB0_244:
	s_or_b64 exec, exec, s[24:25]
	s_waitcnt lgkmcnt(0)
	s_nop 1
	v_mov_b32_dpp v29, v14 quad_perm:[1,0,3,2] row_mask:0xf bank_mask:0xf
	s_and_saveexec_b64 s[24:25], s[0:1]
	s_cbranch_execz .LBB0_246
	v_add_co_u32_e32 v30, vcc, 0x6813000, v24
	s_waitcnt lgkmcnt(0)
	v_cvt_pk_bf16_f32 v29, v14, v29
	s_nop 0
	v_addc_co_u32_e32 v31, vcc, 0, v25, vcc
	global_store_dword v[30:31], v29, off offset:1024
.LBB0_246:
	s_or_b64 exec, exec, s[24:25]
	s_nop 1
	v_mov_b32_dpp v16, v15 quad_perm:[1,0,3,2] row_mask:0xf bank_mask:0xf
	s_and_saveexec_b64 s[24:25], s[0:1]
	s_cbranch_execz .LBB0_248
	v_add_co_u32_e32 v24, vcc, 0x6813000, v24
	s_waitcnt lgkmcnt(0)
	v_cvt_pk_bf16_f32 v16, v15, v16
	s_nop 0
	v_addc_co_u32_e32 v25, vcc, 0, v25, vcc
	global_store_dword v[24:25], v16, off offset:1536

; __device__ __forceinline__ int crow(int r, int hi) { return (r & 3) + 8 * (r >> 2) + 4 * hi; }
; __device__ __forceinline__ unsigned cvtpk(float lo, float hi) { unsigned r; asm volatile("v_cvt_pk_bf16_f32 %0, %1, %2" : "=v"(r) : "v"(lo), "v"(hi)); return r; }
; __device__ __forceinline__ void attn_block(const bf16_t* __restrict__ proj, bf16_t* __restrict__ mixed, int b, int h, int qb, char* lds) {
;     ...
;     if (hi == 0) li_l[r32] = l_reg; asm volatile("s_waitcnt lgkmcnt(0)" ::: "memory");
; #pragma unroll
;     for (int r = 0; r < 16; ++r) { const int orow = crow(r, hi); const float rl = __builtin_amdgcn_rcpf(li_l[orow]);
; #pragma unroll
;         for (int d0 = 0; d0 < 4; ++d0) { const float v = o[d0][r] * rl; const float vn = __shfl_xor(v, 1);
;             if ((r32 & 1) == 0) *(unsigned*)(Op + (size_t)orow * LDO + d0 * 32 + r32) = cvtpk(v, vn); } }
.LBB0_341:
	s_and_saveexec_b64 s[0:1], s[52:53]
	ds_write_b32 v225, v15
	s_or_b64 exec, exec, s[0:1]
	s_waitcnt lgkmcnt(0)
	ds_read_b32 v0, v208
	v_and_b32_e32 v3, 64, v186
	v_xor_b32_e32 v2, 1, v186
	v_add_u32_e32 v6, 64, v3
	v_cmp_lt_i32_e32 vcc, v2, v6
	s_waitcnt lgkmcnt(0)
	v_rcp_f32_e32 v7, v0
	s_add_i32 s0, s64, s83
	v_cndmask_b32_e32 v0, v186, v2, vcc
	s_ashr_i32 s1, s0, 31
	v_lshlrev_b32_e32 v156, 2, v0
	v_mul_f32_e32 v8, v64, v7
	s_lshl_b64 s[0:1], s[0:1], 12
	s_nop 1
	v_mov_b32_dpp v9, v8 quad_perm:[1,0,3,2] row_mask:0xf bank_mask:0xf
	s_add_u32 s0, s81, s0
	s_addc_u32 s1, s82, s1
	v_lshlrev_b32_e32 v0, 1, v210
	v_lshl_add_u64 v[2:3], s[0:1], 0, v[0:1]
	v_lshlrev_b32_e32 v0, 14, v209
	v_cmp_eq_u32_e32 vcc, 0, v211
	v_lshl_add_u64 v[4:5], v[2:3], 0, v[0:1]
	s_and_saveexec_b64 s[0:1], vcc
	s_cbranch_execz .LBB0_345
	s_waitcnt lgkmcnt(0)
	v_cvt_pk_bf16_f32 v0, v8, v9
	global_store_dword v[4:5], v0, off
.LBB0_345:
	s_or_b64 exec, exec, s[0:1]
	v_mul_f32_e32 v0, v48, v7
	s_nop 1
	v_mov_b32_dpp v8, v0 quad_perm:[1,0,3,2] row_mask:0xf bank_mask:0xf
	s_and_saveexec_b64 s[0:1], vcc
	s_cbranch_execz .LBB0_347
	s_waitcnt lgkmcnt(0)
	v_cvt_pk_bf16_f32 v0, v0, v8
	global_store_dword v[4:5], v0, off offset:64
.LBB0_347:
	s_or_b64 exec, exec, s[0:1]
	v_mul_f32_e32 v0, v32, v7
	s_waitcnt lgkmcnt(0)
	s_nop 1
	v_mov_b32_dpp v8, v0 quad_perm:[1,0,3,2] row_mask:0xf bank_mask:0xf
	s_and_saveexec_b64 s[0:1], vcc
	s_cbranch_execz .LBB0_349
	s_waitcnt lgkmcnt(0)
	v_cvt_pk_bf16_f32 v0, v0, v8
	global_store_dword v[4:5], v0, off offset:128
.LBB0_349:
	s_or_b64 exec, exec, s[0:1]
	v_mul_f32_e32 v0, v16, v7
	s_nop 1
	v_mov_b32_dpp v7, v0 quad_perm:[1,0,3,2] row_mask:0xf bank_mask:0xf
	s_and_saveexec_b64 s[0:1], vcc
	s_cbranch_execz .LBB0_351
	s_waitcnt lgkmcnt(0)
	v_cvt_pk_bf16_f32 v0, v0, v7
	global_store_dword v[4:5], v0, off offset:192
.LBB0_351:
	s_or_b64 exec, exec, s[0:1]
	ds_read_b32 v0, v208 offset:4
	s_waitcnt lgkmcnt(0)
	v_rcp_f32_e32 v7, v0
	v_lshl_or_b32 v0, v207, 12, v188
	v_lshl_add_u64 v[4:5], v[2:3], 0, v[0:1]
	v_mul_f32_e32 v8, v65, v7
	s_nop 1
	v_mov_b32_dpp v9, v8 quad_perm:[1,0,3,2] row_mask:0xf bank_mask:0xf
	s_and_saveexec_b64 s[0:1], vcc
	s_cbranch_execz .LBB0_353
	s_waitcnt lgkmcnt(0)
	v_cvt_pk_bf16_f32 v0, v8, v9
	global_store_dword v[4:5], v0, off
.LBB0_353:
	s_or_b64 exec, exec, s[0:1]
	v_mul_f32_e32 v0, v49, v7
	s_nop 1
	v_mov_b32_dpp v8, v0 quad_perm:[1,0,3,2] row_mask:0xf bank_mask:0xf
	s_and_saveexec_b64 s[0:1], vcc
	s_cbranch_execz .LBB0_355
	s_waitcnt lgkmcnt(0)
	v_cvt_pk_bf16_f32 v0, v0, v8
	global_store_dword v[4:5], v0, off offset:64
.LBB0_355:
	s_or_b64 exec, exec, s[0:1]
	v_mul_f32_e32 v0, v33, v7
	s_waitcnt lgkmcnt(0)
	s_nop 1
	v_mov_b32_dpp v8, v0 quad_perm:[1,0,3,2] row_mask:0xf bank_mask:0xf
	s_and_saveexec_b64 s[0:1], vcc
	s_cbranch_execz .LBB0_357
	s_waitcnt lgkmcnt(0)
	v_cvt_pk_bf16_f32 v0, v0, v8
	global_store_dword v[4:5], v0, off offset:128
.LBB0_357:
	s_or_b64 exec, exec, s[0:1]
	v_mul_f32_e32 v0, v17, v7
	s_nop 1
	v_mov_b32_dpp v7, v0 quad_perm:[1,0,3,2] row_mask:0xf bank_mask:0xf
	s_and_saveexec_b64 s[0:1], vcc
	s_cbranch_execz .LBB0_359
	s_waitcnt lgkmcnt(0)
	v_cvt_pk_bf16_f32 v0, v0, v7
	global_store_dword v[4:5], v0, off offset:192
.LBB0_359:
	s_or_b64 exec, exec, s[0:1]
	ds_read_b32 v0, v208 offset:8
	s_waitcnt lgkmcnt(0)
	v_rcp_f32_e32 v7, v0
	v_lshl_or_b32 v0, v207, 12, v189
	v_lshl_add_u64 v[4:5], v[2:3], 0, v[0:1]
	v_mul_f32_e32 v8, v66, v7
	s_nop 1
	v_mov_b32_dpp v9, v8 quad_perm:[1,0,3,2] row_mask:0xf bank_mask:0xf
	s_and_saveexec_b64 s[0:1], vcc
	s_cbranch_execz .LBB0_361
	s_waitcnt lgkmcnt(0)
	v_cvt_pk_bf16_f32 v0, v8, v9
	global_store_dword v[4:5], v0, off
.LBB0_361:
	s_or_b64 exec, exec, s[0:1]
	v_mul_f32_e32 v0, v50, v7
	s_nop 1
	v_mov_b32_dpp v8, v0 quad_perm:[1,0,3,2] row_mask:0xf bank_mask:0xf
	s_and_saveexec_b64 s[0:1], vcc
	s_cbranch_execz .LBB0_363
	s_waitcnt lgkmcnt(0)
	v_cvt_pk_bf16_f32 v0, v0, v8
	global_store_dword v[4:5], v0, off offset:64
.LBB0_363:
	s_or_b64 exec, exec, s[0:1]
	v_mul_f32_e32 v0, v34, v7
	s_waitcnt lgkmcnt(0)
	s_nop 1
	v_mov_b32_dpp v8, v0 quad_perm:[1,0,3,2] row_mask:0xf bank_mask:0xf
	s_and_saveexec_b64 s[0:1], vcc
	s_cbranch_execz .LBB0_365
	s_waitcnt lgkmcnt(0)
	v_cvt_pk_bf16_f32 v0, v0, v8
	global_store_dword v[4:5], v0, off offset:128
.LBB0_365:
	s_or_b64 exec, exec, s[0:1]
	v_mul_f32_e32 v0, v18, v7
	s_nop 1
	v_mov_b32_dpp v7, v0 quad_perm:[1,0,3,2] row_mask:0xf bank_mask:0xf
	s_and_saveexec_b64 s[0:1], vcc
	s_cbranch_execz .LBB0_367
	s_waitcnt lgkmcnt(0)
	v_cvt_pk_bf16_f32 v0, v0, v7
	global_store_dword v[4:5], v0, off offset:192
.LBB0_367:
	s_or_b64 exec, exec, s[0:1]
	ds_read_b32 v0, v208 offset:12
	s_waitcnt lgkmcnt(0)
	v_rcp_f32_e32 v7, v0
	v_lshl_or_b32 v0, v207, 12, v190
	v_lshl_add_u64 v[4:5], v[2:3], 0, v[0:1]
	v_mul_f32_e32 v8, v67, v7
	s_nop 1
	v_mov_b32_dpp v9, v8 quad_perm:[1,0,3,2] row_mask:0xf bank_mask:0xf
	s_and_saveexec_b64 s[0:1], vcc
	s_cbranch_execz .LBB0_369
	s_waitcnt lgkmcnt(0)
	v_cvt_pk_bf16_f32 v0, v8, v9
	global_store_dword v[4:5], v0, off
.LBB0_369:
	s_or_b64 exec, exec, s[0:1]
	v_mul_f32_e32 v0, v51, v7
	s_nop 1
	v_mov_b32_dpp v8, v0 quad_perm:[1,0,3,2] row_mask:0xf bank_mask:0xf
	s_and_saveexec_b64 s[0:1], vcc
	s_cbranch_execz .LBB0_371
	s_waitcnt lgkmcnt(0)
	v_cvt_pk_bf16_f32 v0, v0, v8
	global_store_dword v[4:5], v0, off offset:64
.LBB0_371:
	s_or_b64 exec, exec, s[0:1]
	v_mul_f32_e32 v0, v35, v7
	s_waitcnt lgkmcnt(0)
	s_nop 1
	v_mov_b32_dpp v8, v0 quad_perm:[1,0,3,2] row_mask:0xf bank_mask:0xf
	s_and_saveexec_b64 s[0:1], vcc
	s_cbranch_execz .LBB0_373
	s_waitcnt lgkmcnt(0)
	v_cvt_pk_bf16_f32 v0, v0, v8
	global_store_dword v[4:5], v0, off offset:128
; __device__ __forceinline__ int crow(int r, int hi) { return (r & 3) + 8 * (r >> 2) + 4 * hi; }
; __device__ __forceinline__ unsigned cvtpk(float lo, float hi) { unsigned r; asm volatile("v_cvt_pk_bf16_f32 %0, %1, %2" : "=v"(r) : "v"(lo), "v"(hi)); return r; }
; __device__ __forceinline__ void attn_block(const bf16_t* __restrict__ proj, bf16_t* __restrict__ mixed, int b, int h, int qb, char* lds) {
;     ...
;     if (hi == 0) li_l[r32] = l_reg; asm volatile("s_waitcnt lgkmcnt(0)" ::: "memory");
; #pragma unroll
;     for (int r = 0; r < 16; ++r) { const int orow = crow(r, hi); const float rl = __builtin_amdgcn_rcpf(li_l[orow]);
; #pragma unroll
;         for (int d0 = 0; d0 < 4; ++d0) { const float v = o[d0][r] * rl; const float vn = __shfl_xor(v, 1);
;             if ((r32 & 1) == 0) *(unsigned*)(Op + (size_t)orow * LDO + d0 * 32 + r32) = cvtpk(v, vn); } }
.LBB0_373:
	s_or_b64 exec, exec, s[0:1]
	v_mul_f32_e32 v0, v19, v7
	s_nop 1
	v_mov_b32_dpp v7, v0 quad_perm:[1,0,3,2] row_mask:0xf bank_mask:0xf
	s_and_saveexec_b64 s[0:1], vcc
	s_cbranch_execz .LBB0_375
	s_waitcnt lgkmcnt(0)
	v_cvt_pk_bf16_f32 v0, v0, v7
	global_store_dword v[4:5], v0, off offset:192
.LBB0_375:
	s_or_b64 exec, exec, s[0:1]
	ds_read_b32 v0, v208 offset:32
	s_waitcnt lgkmcnt(0)
	v_rcp_f32_e32 v7, v0
	v_lshl_or_b32 v0, v207, 12, v191
	v_lshl_add_u64 v[4:5], v[2:3], 0, v[0:1]
	v_mul_f32_e32 v8, v68, v7
	s_nop 1
	v_mov_b32_dpp v9, v8 quad_perm:[1,0,3,2] row_mask:0xf bank_mask:0xf
	s_and_saveexec_b64 s[0:1], vcc
	s_cbranch_execz .LBB0_377
	s_waitcnt lgkmcnt(0)
	v_cvt_pk_bf16_f32 v0, v8, v9
	global_store_dword v[4:5], v0, off
.LBB0_377:
	s_or_b64 exec, exec, s[0:1]
	v_mul_f32_e32 v0, v52, v7
	s_nop 1
	v_mov_b32_dpp v8, v0 quad_perm:[1,0,3,2] row_mask:0xf bank_mask:0xf
	s_and_saveexec_b64 s[0:1], vcc
	s_cbranch_execz .LBB0_379
	s_waitcnt lgkmcnt(0)
	v_cvt_pk_bf16_f32 v0, v0, v8
	global_store_dword v[4:5], v0, off offset:64
.LBB0_379:
	s_or_b64 exec, exec, s[0:1]
	v_mul_f32_e32 v0, v36, v7
	s_waitcnt lgkmcnt(0)
	s_nop 1
	v_mov_b32_dpp v8, v0 quad_perm:[1,0,3,2] row_mask:0xf bank_mask:0xf
	s_and_saveexec_b64 s[0:1], vcc
	s_cbranch_execz .LBB0_381
	s_waitcnt lgkmcnt(0)
	v_cvt_pk_bf16_f32 v0, v0, v8
	global_store_dword v[4:5], v0, off offset:128
.LBB0_381:
	s_or_b64 exec, exec, s[0:1]
	v_mul_f32_e32 v0, v20, v7
	s_nop 1
	v_mov_b32_dpp v7, v0 quad_perm:[1,0,3,2] row_mask:0xf bank_mask:0xf
	s_and_saveexec_b64 s[0:1], vcc
	s_cbranch_execz .LBB0_383
	s_waitcnt lgkmcnt(0)
	v_cvt_pk_bf16_f32 v0, v0, v7
	global_store_dword v[4:5], v0, off offset:192
.LBB0_383:
	s_or_b64 exec, exec, s[0:1]
	ds_read_b32 v0, v208 offset:36
	s_waitcnt lgkmcnt(0)
	v_rcp_f32_e32 v7, v0
	v_lshl_or_b32 v0, v207, 12, v192
	v_lshl_add_u64 v[4:5], v[2:3], 0, v[0:1]
	v_mul_f32_e32 v8, v69, v7
	s_nop 1
	v_mov_b32_dpp v9, v8 quad_perm:[1,0,3,2] row_mask:0xf bank_mask:0xf
	s_and_saveexec_b64 s[0:1], vcc
	s_cbranch_execz .LBB0_385
	s_waitcnt lgkmcnt(0)
	v_cvt_pk_bf16_f32 v0, v8, v9
	global_store_dword v[4:5], v0, off
.LBB0_385:
	s_or_b64 exec, exec, s[0:1]
	v_mul_f32_e32 v0, v53, v7
	s_nop 1
	v_mov_b32_dpp v8, v0 quad_perm:[1,0,3,2] row_mask:0xf bank_mask:0xf
	s_and_saveexec_b64 s[0:1], vcc
	s_cbranch_execz .LBB0_387
	s_waitcnt lgkmcnt(0)
	v_cvt_pk_bf16_f32 v0, v0, v8
	global_store_dword v[4:5], v0, off offset:64
.LBB0_387:
	s_or_b64 exec, exec, s[0:1]
	v_mul_f32_e32 v0, v37, v7
	s_waitcnt lgkmcnt(0)
	s_nop 1
	v_mov_b32_dpp v8, v0 quad_perm:[1,0,3,2] row_mask:0xf bank_mask:0xf
	s_and_saveexec_b64 s[0:1], vcc
	s_cbranch_execz .LBB0_389
	s_waitcnt lgkmcnt(0)
	v_cvt_pk_bf16_f32 v0, v0, v8
	global_store_dword v[4:5], v0, off offset:128
.LBB0_389:
	s_or_b64 exec, exec, s[0:1]
	v_mul_f32_e32 v0, v21, v7
	s_nop 1
	v_mov_b32_dpp v7, v0 quad_perm:[1,0,3,2] row_mask:0xf bank_mask:0xf
	s_and_saveexec_b64 s[0:1], vcc
	s_cbranch_execz .LBB0_391
	s_waitcnt lgkmcnt(0)
	v_cvt_pk_bf16_f32 v0, v0, v7
	global_store_dword v[4:5], v0, off offset:192
.LBB0_391:
	s_or_b64 exec, exec, s[0:1]
	ds_read_b32 v0, v208 offset:40
	s_waitcnt lgkmcnt(0)
	v_rcp_f32_e32 v7, v0
	v_lshl_or_b32 v0, v207, 12, v193
	v_lshl_add_u64 v[4:5], v[2:3], 0, v[0:1]
	v_mul_f32_e32 v8, v70, v7
	s_nop 1
	v_mov_b32_dpp v9, v8 quad_perm:[1,0,3,2] row_mask:0xf bank_mask:0xf
	s_and_saveexec_b64 s[0:1], vcc
	s_cbranch_execz .LBB0_393
	s_waitcnt lgkmcnt(0)
	v_cvt_pk_bf16_f32 v0, v8, v9
	global_store_dword v[4:5], v0, off
.LBB0_393:
	s_or_b64 exec, exec, s[0:1]
	v_mul_f32_e32 v0, v54, v7
	s_nop 1
	v_mov_b32_dpp v8, v0 quad_perm:[1,0,3,2] row_mask:0xf bank_mask:0xf
	s_and_saveexec_b64 s[0:1], vcc
	s_cbranch_execz .LBB0_395
	s_waitcnt lgkmcnt(0)
	v_cvt_pk_bf16_f32 v0, v0, v8
	global_store_dword v[4:5], v0, off offset:64
.LBB0_395:
	s_or_b64 exec, exec, s[0:1]
	v_mul_f32_e32 v0, v38, v7
	s_waitcnt lgkmcnt(0)
	s_nop 1
	v_mov_b32_dpp v8, v0 quad_perm:[1,0,3,2] row_mask:0xf bank_mask:0xf
	s_and_saveexec_b64 s[0:1], vcc
	s_cbranch_execz .LBB0_397
	s_waitcnt lgkmcnt(0)
	v_cvt_pk_bf16_f32 v0, v0, v8
	global_store_dword v[4:5], v0, off offset:128
.LBB0_397:
	s_or_b64 exec, exec, s[0:1]
	v_mul_f32_e32 v0, v22, v7
	s_nop 1
	v_mov_b32_dpp v7, v0 quad_perm:[1,0,3,2] row_mask:0xf bank_mask:0xf
	s_and_saveexec_b64 s[0:1], vcc
	s_cbranch_execz .LBB0_399
	s_waitcnt lgkmcnt(0)
	v_cvt_pk_bf16_f32 v0, v0, v7
	global_store_dword v[4:5], v0, off offset:192
.LBB0_399:
	s_or_b64 exec, exec, s[0:1]
	ds_read_b32 v0, v208 offset:44
	s_waitcnt lgkmcnt(0)
	v_rcp_f32_e32 v7, v0
	v_lshl_or_b32 v0, v207, 12, v194
	v_lshl_add_u64 v[4:5], v[2:3], 0, v[0:1]
	v_mul_f32_e32 v8, v71, v7
	s_nop 1
	v_mov_b32_dpp v9, v8 quad_perm:[1,0,3,2] row_mask:0xf bank_mask:0xf
	s_and_saveexec_b64 s[0:1], vcc
	s_cbranch_execz .LBB0_401
	s_waitcnt lgkmcnt(0)
	v_cvt_pk_bf16_f32 v0, v8, v9
	global_store_dword v[4:5], v0, off
.LBB0_401:
	s_or_b64 exec, exec, s[0:1]
	v_mul_f32_e32 v0, v55, v7
	s_nop 1
	v_mov_b32_dpp v8, v0 quad_perm:[1,0,3,2] row_mask:0xf bank_mask:0xf
	s_and_saveexec_b64 s[0:1], vcc
	s_cbranch_execz .LBB0_403
	s_waitcnt lgkmcnt(0)
	v_cvt_pk_bf16_f32 v0, v0, v8
	global_store_dword v[4:5], v0, off offset:64
.LBB0_403:
	s_or_b64 exec, exec, s[0:1]
	v_mul_f32_e32 v0, v39, v7
	s_waitcnt lgkmcnt(0)
	s_nop 1
	v_mov_b32_dpp v8, v0 quad_perm:[1,0,3,2] row_mask:0xf bank_mask:0xf
	s_and_saveexec_b64 s[0:1], vcc
	s_cbranch_execz .LBB0_405
	s_waitcnt lgkmcnt(0)
	v_cvt_pk_bf16_f32 v0, v0, v8
	global_store_dword v[4:5], v0, off offset:128
; __device__ __forceinline__ int crow(int r, int hi) { return (r & 3) + 8 * (r >> 2) + 4 * hi; }
; __device__ __forceinline__ unsigned cvtpk(float lo, float hi) { unsigned r; asm volatile("v_cvt_pk_bf16_f32 %0, %1, %2" : "=v"(r) : "v"(lo), "v"(hi)); return r; }
; __device__ __forceinline__ void attn_block(const bf16_t* __restrict__ proj, bf16_t* __restrict__ mixed, int b, int h, int qb, char* lds) {
;     ...
;     if (hi == 0) li_l[r32] = l_reg; asm volatile("s_waitcnt lgkmcnt(0)" ::: "memory");
; #pragma unroll
;     for (int r = 0; r < 16; ++r) { const int orow = crow(r, hi); const float rl = __builtin_amdgcn_rcpf(li_l[orow]);
; #pragma unroll
;         for (int d0 = 0; d0 < 4; ++d0) { const float v = o[d0][r] * rl; const float vn = __shfl_xor(v, 1);
;             if ((r32 & 1) == 0) *(unsigned*)(Op + (size_t)orow * LDO + d0 * 32 + r32) = cvtpk(v, vn); } }
.LBB0_405:
	s_or_b64 exec, exec, s[0:1]
	v_mul_f32_e32 v0, v23, v7
	s_nop 1
	v_mov_b32_dpp v7, v0 quad_perm:[1,0,3,2] row_mask:0xf bank_mask:0xf
	s_and_saveexec_b64 s[0:1], vcc
	s_cbranch_execz .LBB0_407
	s_waitcnt lgkmcnt(0)
	v_cvt_pk_bf16_f32 v0, v0, v7
	global_store_dword v[4:5], v0, off offset:192
.LBB0_407:
	s_or_b64 exec, exec, s[0:1]
	ds_read_b32 v0, v208 offset:64
	s_waitcnt lgkmcnt(0)
	v_rcp_f32_e32 v7, v0
	v_lshl_or_b32 v0, v207, 12, v195
	v_lshl_add_u64 v[4:5], v[2:3], 0, v[0:1]
	v_mul_f32_e32 v8, v72, v7
	s_nop 1
	v_mov_b32_dpp v9, v8 quad_perm:[1,0,3,2] row_mask:0xf bank_mask:0xf
	s_and_saveexec_b64 s[0:1], vcc
	s_cbranch_execz .LBB0_409
	s_waitcnt lgkmcnt(0)
	v_cvt_pk_bf16_f32 v0, v8, v9
	global_store_dword v[4:5], v0, off
.LBB0_409:
	s_or_b64 exec, exec, s[0:1]
	v_mul_f32_e32 v0, v56, v7
	s_nop 1
	v_mov_b32_dpp v8, v0 quad_perm:[1,0,3,2] row_mask:0xf bank_mask:0xf
	s_and_saveexec_b64 s[0:1], vcc
	s_cbranch_execz .LBB0_411
	s_waitcnt lgkmcnt(0)
	v_cvt_pk_bf16_f32 v0, v0, v8
	global_store_dword v[4:5], v0, off offset:64
.LBB0_411:
	s_or_b64 exec, exec, s[0:1]
	v_mul_f32_e32 v0, v40, v7
	s_waitcnt lgkmcnt(0)
	s_nop 1
	v_mov_b32_dpp v8, v0 quad_perm:[1,0,3,2] row_mask:0xf bank_mask:0xf
	s_and_saveexec_b64 s[0:1], vcc
	s_cbranch_execz .LBB0_413
	s_waitcnt lgkmcnt(0)
	v_cvt_pk_bf16_f32 v0, v0, v8
	global_store_dword v[4:5], v0, off offset:128
.LBB0_413:
	s_or_b64 exec, exec, s[0:1]
	v_mul_f32_e32 v0, v24, v7
	s_nop 1
	v_mov_b32_dpp v7, v0 quad_perm:[1,0,3,2] row_mask:0xf bank_mask:0xf
	s_and_saveexec_b64 s[0:1], vcc
	s_cbranch_execz .LBB0_415
	s_waitcnt lgkmcnt(0)
	v_cvt_pk_bf16_f32 v0, v0, v7
	global_store_dword v[4:5], v0, off offset:192
.LBB0_415:
	s_or_b64 exec, exec, s[0:1]
	ds_read_b32 v0, v208 offset:68
	s_waitcnt lgkmcnt(0)
	v_rcp_f32_e32 v7, v0
	v_lshl_or_b32 v0, v207, 12, v196
	v_lshl_add_u64 v[4:5], v[2:3], 0, v[0:1]
	v_mul_f32_e32 v8, v73, v7
	s_nop 1
	v_mov_b32_dpp v9, v8 quad_perm:[1,0,3,2] row_mask:0xf bank_mask:0xf
	s_and_saveexec_b64 s[0:1], vcc
	s_cbranch_execz .LBB0_417
	s_waitcnt lgkmcnt(0)
	v_cvt_pk_bf16_f32 v0, v8, v9
	global_store_dword v[4:5], v0, off
.LBB0_417:
	s_or_b64 exec, exec, s[0:1]
	v_mul_f32_e32 v0, v57, v7
	s_nop 1
	v_mov_b32_dpp v8, v0 quad_perm:[1,0,3,2] row_mask:0xf bank_mask:0xf
	s_and_saveexec_b64 s[0:1], vcc
	s_cbranch_execz .LBB0_419
	s_waitcnt lgkmcnt(0)
	v_cvt_pk_bf16_f32 v0, v0, v8
	global_store_dword v[4:5], v0, off offset:64
.LBB0_419:
	s_or_b64 exec, exec, s[0:1]
	v_mul_f32_e32 v0, v41, v7
	s_waitcnt lgkmcnt(0)
	s_nop 1
	v_mov_b32_dpp v8, v0 quad_perm:[1,0,3,2] row_mask:0xf bank_mask:0xf
	s_and_saveexec_b64 s[0:1], vcc
	s_cbranch_execz .LBB0_421
	s_waitcnt lgkmcnt(0)
	v_cvt_pk_bf16_f32 v0, v0, v8
	global_store_dword v[4:5], v0, off offset:128
.LBB0_421:
	s_or_b64 exec, exec, s[0:1]
	v_mul_f32_e32 v0, v25, v7
	s_nop 1
	v_mov_b32_dpp v7, v0 quad_perm:[1,0,3,2] row_mask:0xf bank_mask:0xf
	s_and_saveexec_b64 s[0:1], vcc
	s_cbranch_execz .LBB0_423
	s_waitcnt lgkmcnt(0)
	v_cvt_pk_bf16_f32 v0, v0, v7
	global_store_dword v[4:5], v0, off offset:192
.LBB0_423:
	s_or_b64 exec, exec, s[0:1]
	ds_read_b32 v0, v208 offset:72
	s_waitcnt lgkmcnt(0)
	v_rcp_f32_e32 v7, v0
	v_lshl_or_b32 v0, v207, 12, v197
	v_lshl_add_u64 v[4:5], v[2:3], 0, v[0:1]
	v_mul_f32_e32 v8, v74, v7
	s_nop 1
	v_mov_b32_dpp v9, v8 quad_perm:[1,0,3,2] row_mask:0xf bank_mask:0xf
	s_and_saveexec_b64 s[0:1], vcc
	s_cbranch_execz .LBB0_425
	s_waitcnt lgkmcnt(0)
	v_cvt_pk_bf16_f32 v0, v8, v9
	global_store_dword v[4:5], v0, off
.LBB0_425:
	s_or_b64 exec, exec, s[0:1]
	v_mul_f32_e32 v0, v58, v7
	s_nop 1
	v_mov_b32_dpp v8, v0 quad_perm:[1,0,3,2] row_mask:0xf bank_mask:0xf
	s_and_saveexec_b64 s[0:1], vcc
	s_cbranch_execz .LBB0_427
	s_waitcnt lgkmcnt(0)
	v_cvt_pk_bf16_f32 v0, v0, v8
	global_store_dword v[4:5], v0, off offset:64
.LBB0_427:
	s_or_b64 exec, exec, s[0:1]
	v_mul_f32_e32 v0, v42, v7
	s_waitcnt lgkmcnt(0)
	s_nop 1
	v_mov_b32_dpp v8, v0 quad_perm:[1,0,3,2] row_mask:0xf bank_mask:0xf
	s_and_saveexec_b64 s[0:1], vcc
	s_cbranch_execz .LBB0_429
	s_waitcnt lgkmcnt(0)
	v_cvt_pk_bf16_f32 v0, v0, v8
	global_store_dword v[4:5], v0, off offset:128
.LBB0_429:
	s_or_b64 exec, exec, s[0:1]
	v_mul_f32_e32 v0, v26, v7
	s_nop 1
	v_mov_b32_dpp v7, v0 quad_perm:[1,0,3,2] row_mask:0xf bank_mask:0xf
	s_and_saveexec_b64 s[0:1], vcc
	s_cbranch_execz .LBB0_431
	s_waitcnt lgkmcnt(0)
	v_cvt_pk_bf16_f32 v0, v0, v7
	global_store_dword v[4:5], v0, off offset:192
.LBB0_431:
	s_or_b64 exec, exec, s[0:1]
	ds_read_b32 v0, v208 offset:76
	s_waitcnt lgkmcnt(0)
	v_rcp_f32_e32 v7, v0
	v_lshl_or_b32 v0, v207, 12, v198
	v_lshl_add_u64 v[4:5], v[2:3], 0, v[0:1]
	v_mul_f32_e32 v8, v75, v7
	s_nop 1
	v_mov_b32_dpp v9, v8 quad_perm:[1,0,3,2] row_mask:0xf bank_mask:0xf
	s_and_saveexec_b64 s[0:1], vcc
	s_cbranch_execz .LBB0_433
	s_waitcnt lgkmcnt(0)
	v_cvt_pk_bf16_f32 v0, v8, v9
	global_store_dword v[4:5], v0, off
.LBB0_433:
	s_or_b64 exec, exec, s[0:1]
	v_mul_f32_e32 v0, v59, v7
	s_nop 1
	v_mov_b32_dpp v8, v0 quad_perm:[1,0,3,2] row_mask:0xf bank_mask:0xf
	s_and_saveexec_b64 s[0:1], vcc
	s_cbranch_execz .LBB0_435
	s_waitcnt lgkmcnt(0)
	v_cvt_pk_bf16_f32 v0, v0, v8
	global_store_dword v[4:5], v0, off offset:64
.LBB0_435:
	s_or_b64 exec, exec, s[0:1]
	v_mul_f32_e32 v0, v43, v7
	s_waitcnt lgkmcnt(0)
	s_nop 1
	v_mov_b32_dpp v8, v0 quad_perm:[1,0,3,2] row_mask:0xf bank_mask:0xf
	s_and_saveexec_b64 s[0:1], vcc
	s_cbranch_execz .LBB0_437
	s_waitcnt lgkmcnt(0)
	v_cvt_pk_bf16_f32 v0, v0, v8
	global_store_dword v[4:5], v0, off offset:128
; __device__ __forceinline__ int crow(int r, int hi) { return (r & 3) + 8 * (r >> 2) + 4 * hi; }
; __device__ __forceinline__ unsigned cvtpk(float lo, float hi) { unsigned r; asm volatile("v_cvt_pk_bf16_f32 %0, %1, %2" : "=v"(r) : "v"(lo), "v"(hi)); return r; }
; __device__ __forceinline__ void attn_block(const bf16_t* __restrict__ proj, bf16_t* __restrict__ mixed, int b, int h, int qb, char* lds) {
;     ...
;     if (hi == 0) li_l[r32] = l_reg; asm volatile("s_waitcnt lgkmcnt(0)" ::: "memory");
; #pragma unroll
;     for (int r = 0; r < 16; ++r) { const int orow = crow(r, hi); const float rl = __builtin_amdgcn_rcpf(li_l[orow]);
; #pragma unroll
;         for (int d0 = 0; d0 < 4; ++d0) { const float v = o[d0][r] * rl; const float vn = __shfl_xor(v, 1);
;             if ((r32 & 1) == 0) *(unsigned*)(Op + (size_t)orow * LDO + d0 * 32 + r32) = cvtpk(v, vn); } }
.LBB0_437:
	s_or_b64 exec, exec, s[0:1]
	v_mul_f32_e32 v0, v27, v7
	s_nop 1
	v_mov_b32_dpp v7, v0 quad_perm:[1,0,3,2] row_mask:0xf bank_mask:0xf
	s_and_saveexec_b64 s[0:1], vcc
	s_cbranch_execz .LBB0_439
	s_waitcnt lgkmcnt(0)
	v_cvt_pk_bf16_f32 v0, v0, v7
	global_store_dword v[4:5], v0, off offset:192
.LBB0_439:
	s_or_b64 exec, exec, s[0:1]
	ds_read_b32 v0, v208 offset:96
	s_waitcnt lgkmcnt(0)
	v_rcp_f32_e32 v7, v0
	v_lshl_or_b32 v0, v207, 12, v199
	v_lshl_add_u64 v[4:5], v[2:3], 0, v[0:1]
	v_mul_f32_e32 v8, v76, v7
	s_nop 1
	v_mov_b32_dpp v9, v8 quad_perm:[1,0,3,2] row_mask:0xf bank_mask:0xf
	s_and_saveexec_b64 s[0:1], vcc
	s_cbranch_execz .LBB0_441
	s_waitcnt lgkmcnt(0)
	v_cvt_pk_bf16_f32 v0, v8, v9
	global_store_dword v[4:5], v0, off
.LBB0_441:
	s_or_b64 exec, exec, s[0:1]
	v_mul_f32_e32 v0, v60, v7
	s_nop 1
	v_mov_b32_dpp v8, v0 quad_perm:[1,0,3,2] row_mask:0xf bank_mask:0xf
	s_and_saveexec_b64 s[0:1], vcc
	s_cbranch_execz .LBB0_443
	s_waitcnt lgkmcnt(0)
	v_cvt_pk_bf16_f32 v0, v0, v8
	global_store_dword v[4:5], v0, off offset:64
.LBB0_443:
	s_or_b64 exec, exec, s[0:1]
	v_mul_f32_e32 v0, v44, v7
	s_waitcnt lgkmcnt(0)
	s_nop 1
	v_mov_b32_dpp v8, v0 quad_perm:[1,0,3,2] row_mask:0xf bank_mask:0xf
	s_and_saveexec_b64 s[0:1], vcc
	s_cbranch_execz .LBB0_445
	s_waitcnt lgkmcnt(0)
	v_cvt_pk_bf16_f32 v0, v0, v8
	global_store_dword v[4:5], v0, off offset:128
.LBB0_445:
	s_or_b64 exec, exec, s[0:1]
	v_mul_f32_e32 v0, v28, v7
	s_nop 1
	v_mov_b32_dpp v7, v0 quad_perm:[1,0,3,2] row_mask:0xf bank_mask:0xf
	s_and_saveexec_b64 s[0:1], vcc
	s_cbranch_execz .LBB0_447
	s_waitcnt lgkmcnt(0)
	v_cvt_pk_bf16_f32 v0, v0, v7
	global_store_dword v[4:5], v0, off offset:192
.LBB0_447:
	s_or_b64 exec, exec, s[0:1]
	ds_read_b32 v0, v208 offset:100
	s_waitcnt lgkmcnt(0)
	v_rcp_f32_e32 v7, v0
	v_lshl_or_b32 v0, v207, 12, v200
	v_lshl_add_u64 v[4:5], v[2:3], 0, v[0:1]
	v_mul_f32_e32 v8, v77, v7
	s_nop 1
	v_mov_b32_dpp v9, v8 quad_perm:[1,0,3,2] row_mask:0xf bank_mask:0xf
	s_and_saveexec_b64 s[0:1], vcc
	s_cbranch_execz .LBB0_449
	s_waitcnt lgkmcnt(0)
	v_cvt_pk_bf16_f32 v0, v8, v9
	global_store_dword v[4:5], v0, off
.LBB0_449:
	s_or_b64 exec, exec, s[0:1]
	v_mul_f32_e32 v0, v61, v7
	s_nop 1
	v_mov_b32_dpp v8, v0 quad_perm:[1,0,3,2] row_mask:0xf bank_mask:0xf
	s_and_saveexec_b64 s[0:1], vcc
	s_cbranch_execz .LBB0_451
	s_waitcnt lgkmcnt(0)
	v_cvt_pk_bf16_f32 v0, v0, v8
	global_store_dword v[4:5], v0, off offset:64
.LBB0_451:
	s_or_b64 exec, exec, s[0:1]
	v_mul_f32_e32 v0, v45, v7
	s_waitcnt lgkmcnt(0)
	s_nop 1
	v_mov_b32_dpp v8, v0 quad_perm:[1,0,3,2] row_mask:0xf bank_mask:0xf
	s_and_saveexec_b64 s[0:1], vcc
	s_cbranch_execz .LBB0_453
	s_waitcnt lgkmcnt(0)
	v_cvt_pk_bf16_f32 v0, v0, v8
	global_store_dword v[4:5], v0, off offset:128
.LBB0_453:
	s_or_b64 exec, exec, s[0:1]
	v_mul_f32_e32 v0, v29, v7
	s_nop 1
	v_mov_b32_dpp v7, v0 quad_perm:[1,0,3,2] row_mask:0xf bank_mask:0xf
	s_and_saveexec_b64 s[0:1], vcc
	s_cbranch_execz .LBB0_455
	s_waitcnt lgkmcnt(0)
	v_cvt_pk_bf16_f32 v0, v0, v7
	global_store_dword v[4:5], v0, off offset:192
.LBB0_455:
	s_or_b64 exec, exec, s[0:1]
	ds_read_b32 v0, v208 offset:104
	s_waitcnt lgkmcnt(0)
	v_rcp_f32_e32 v7, v0
	v_lshl_or_b32 v0, v207, 12, v201
	v_lshl_add_u64 v[4:5], v[2:3], 0, v[0:1]
	v_mul_f32_e32 v8, v78, v7
	s_nop 1
	v_mov_b32_dpp v9, v8 quad_perm:[1,0,3,2] row_mask:0xf bank_mask:0xf
	s_and_saveexec_b64 s[0:1], vcc
	s_cbranch_execz .LBB0_457
	s_waitcnt lgkmcnt(0)
	v_cvt_pk_bf16_f32 v0, v8, v9
	global_store_dword v[4:5], v0, off
.LBB0_457:
	s_or_b64 exec, exec, s[0:1]
	v_mul_f32_e32 v0, v62, v7
	s_nop 1
	v_mov_b32_dpp v8, v0 quad_perm:[1,0,3,2] row_mask:0xf bank_mask:0xf
	s_and_saveexec_b64 s[0:1], vcc
	s_cbranch_execz .LBB0_459
	s_waitcnt lgkmcnt(0)
	v_cvt_pk_bf16_f32 v0, v0, v8
	global_store_dword v[4:5], v0, off offset:64
.LBB0_459:
	s_or_b64 exec, exec, s[0:1]
	v_mul_f32_e32 v0, v46, v7
	s_waitcnt lgkmcnt(0)
	s_nop 1
	v_mov_b32_dpp v8, v0 quad_perm:[1,0,3,2] row_mask:0xf bank_mask:0xf
	s_and_saveexec_b64 s[0:1], vcc
	s_cbranch_execz .LBB0_461
	s_waitcnt lgkmcnt(0)
	v_cvt_pk_bf16_f32 v0, v0, v8
	global_store_dword v[4:5], v0, off offset:128
.LBB0_461:
	s_or_b64 exec, exec, s[0:1]
	v_mul_f32_e32 v0, v30, v7
	s_nop 1
	v_mov_b32_dpp v7, v0 quad_perm:[1,0,3,2] row_mask:0xf bank_mask:0xf
	s_and_saveexec_b64 s[0:1], vcc
	s_cbranch_execz .LBB0_463
	s_waitcnt lgkmcnt(0)
	v_cvt_pk_bf16_f32 v0, v0, v7
	global_store_dword v[4:5], v0, off offset:192
.LBB0_463:
	s_or_b64 exec, exec, s[0:1]
	ds_read_b32 v0, v208 offset:108
	s_waitcnt lgkmcnt(0)
	v_rcp_f32_e32 v4, v0
	v_lshl_or_b32 v0, v207, 12, v202
	v_lshl_add_u64 v[2:3], v[2:3], 0, v[0:1]
	v_mul_f32_e32 v5, v79, v4
	s_nop 1
	v_mov_b32_dpp v7, v5 quad_perm:[1,0,3,2] row_mask:0xf bank_mask:0xf
	s_and_saveexec_b64 s[0:1], vcc
	s_cbranch_execz .LBB0_465
	s_waitcnt lgkmcnt(0)
	v_cvt_pk_bf16_f32 v0, v5, v7
	global_store_dword v[2:3], v0, off
.LBB0_465:
	s_or_b64 exec, exec, s[0:1]
	v_mul_f32_e32 v0, v63, v4
	s_nop 1
	v_mov_b32_dpp v5, v0 quad_perm:[1,0,3,2] row_mask:0xf bank_mask:0xf
	s_and_saveexec_b64 s[0:1], vcc
	s_cbranch_execz .LBB0_467
	s_waitcnt lgkmcnt(0)
	v_cvt_pk_bf16_f32 v0, v0, v5
	global_store_dword v[2:3], v0, off offset:64
.LBB0_467:
	s_or_b64 exec, exec, s[0:1]
	v_mul_f32_e32 v0, v47, v4
	s_waitcnt lgkmcnt(0)
	s_nop 1
	v_mov_b32_dpp v5, v0 quad_perm:[1,0,3,2] row_mask:0xf bank_mask:0xf
	s_and_saveexec_b64 s[0:1], vcc
	s_cbranch_execz .LBB0_469
	s_waitcnt lgkmcnt(0)
	v_cvt_pk_bf16_f32 v0, v0, v5
	global_store_dword v[2:3], v0, off offset:128
.LBB0_469:
	s_or_b64 exec, exec, s[0:1]
	v_mul_f32_e32 v0, v31, v4
	s_nop 1
	v_mov_b32_dpp v4, v0 quad_perm:[1,0,3,2] row_mask:0xf bank_mask:0xf
	s_and_saveexec_b64 s[0:1], vcc
	s_cbranch_execz .LBB0_309
	s_waitcnt lgkmcnt(0)
	v_cvt_pk_bf16_f32 v0, v0, v4
	global_store_dword v[2:3], v0, off offset:192
	s_branch .LBB0_309

; __device__ __forceinline__ int crow(int r, int hi) { return (r & 3) + 8 * (r >> 2) + 4 * hi; }
; __device__ __forceinline__ void ret_block(const bf16_t* __restrict__ proj, const bf16_t* __restrict__ state, bf16_t* __restrict__ mixed, int b, int h, int qb, char* lds) {
;     ...
;     bf16_t graw[16][4];
; #pragma unroll
;     for (int r = 0; r < 16; ++r)
; #pragma unroll
;         for (int d0 = 0; d0 < 4; ++d0) graw[r][d0] = Gp[(size_t)crow(r, hi) * LDQ + d0 * 32 + r32];
;     float ssr[16];
; #pragma unroll
;     for (int r = 0; r < 16; ++r) { float s = 0.f;
; #pragma unroll
;         for (int d0 = 0; d0 < 4; ++d0) s += o[d0][r] * o[d0][r];
;         s += __shfl_xor(s, 1); s += __shfl_xor(s, 2); s += __shfl_xor(s, 4); s += __shfl_xor(s, 8); s += __shfl_xor(s, 16);
;         ssr[r] = s; }
.LBB0_486:
	s_lshl_b32 s4, s52, 7
	s_ashr_i32 s5, s4, 31
	s_mul_i32 s0, s51, 0x3800
	s_add_u32 s6, s36, s0
	s_addc_u32 s7, s37, 0
	s_lshl_b64 s[0:1], s[4:5], 1
	s_add_u32 s6, s6, s0
	s_addc_u32 s7, s7, s1
	v_lshlrev_b32_e32 v152, 1, v194
	v_lshl_add_u64 v[64:65], s[6:7], 0, v[152:153]
	s_mov_b64 s[6:7], 0x1800
	v_lshl_add_u64 v[64:65], v[64:65], 0, s[6:7]
	v_mul_u32_u24_e32 v66, 0xe000, v192
	v_mov_b32_e32 v67, v153
	v_lshl_add_u64 v[66:67], v[64:65], 0, v[66:67]
	v_or_b32_e32 v196, 1, v191
	global_load_ushort v201, v[66:67], off
	global_load_ushort v200, v[66:67], off offset:64
	global_load_ushort v199, v[66:67], off offset:128
	global_load_ushort v198, v[66:67], off offset:192
	v_mul_u32_u24_e32 v66, 0x3800, v196
	v_mov_b32_e32 v67, v153
	v_lshl_add_u64 v[66:67], v[64:65], 0, v[66:67]
	s_mov_b64 s[6:7], 0x3800
	global_load_ushort v197, v[66:67], off
	global_load_ushort v195, v[66:67], off offset:64
	global_load_ushort v155, v[66:67], off offset:128
	global_load_ushort v154, v[66:67], off offset:192
	v_lshl_add_u64 v[68:69], v[66:67], 0, s[6:7]
	v_add_co_u32_e32 v66, vcc, s42, v66
	v_pk_mul_f32 v[78:79], v[16:17], v[16:17]
	s_nop 0
	v_addc_co_u32_e32 v67, vcc, 0, v67, vcc
	global_load_ushort v151, v[66:67], off offset:2048
	global_load_ushort v150, v[68:69], off offset:64
	global_load_ushort v149, v[68:69], off offset:128
	global_load_ushort v148, v[68:69], off offset:192
	v_mad_u32_u24 v66, v196, s33, v162
	v_mov_b32_e32 v67, v153
	v_lshl_add_u64 v[66:67], v[64:65], 0, v[66:67]
	global_load_ushort v147, v[66:67], off
	global_load_ushort v146, v[66:67], off offset:64
	global_load_ushort v145, v[66:67], off offset:128
	global_load_ushort v144, v[66:67], off offset:192
	v_mad_u32_u24 v66, v196, s33, v163
	v_mov_b32_e32 v67, v153
	v_lshl_add_u64 v[66:67], v[64:65], 0, v[66:67]
	global_load_ushort v143, v[66:67], off
	global_load_ushort v142, v[66:67], off offset:64
	global_load_ushort v141, v[66:67], off offset:128
	global_load_ushort v140, v[66:67], off offset:192
	v_mad_u32_u24 v66, v196, s33, v164
	v_mov_b32_e32 v67, v153
	v_lshl_add_u64 v[66:67], v[64:65], 0, v[66:67]
	global_load_ushort v139, v[66:67], off
	global_load_ushort v138, v[66:67], off offset:64
	global_load_ushort v137, v[66:67], off offset:128
	global_load_ushort v136, v[66:67], off offset:192
	v_mad_u32_u24 v66, v196, s33, v165
	v_mov_b32_e32 v67, v153
	v_lshl_add_u64 v[66:67], v[64:65], 0, v[66:67]
	global_load_ushort v135, v[66:67], off
	global_load_ushort v134, v[66:67], off offset:64
	global_load_ushort v133, v[66:67], off offset:128
	global_load_ushort v132, v[66:67], off offset:192
	v_mad_u32_u24 v66, v196, s33, v166
	v_mov_b32_e32 v67, v153
	v_lshl_add_u64 v[66:67], v[64:65], 0, v[66:67]
	global_load_ushort v131, v[66:67], off
	global_load_ushort v130, v[66:67], off offset:64
	global_load_ushort v129, v[66:67], off offset:128
	global_load_ushort v128, v[66:67], off offset:192
	v_mad_u32_u24 v66, v196, s33, v167
	v_mov_b32_e32 v67, v153
	v_lshl_add_u64 v[66:67], v[64:65], 0, v[66:67]
	global_load_ushort v127, v[66:67], off
	global_load_ushort v126, v[66:67], off offset:64
	global_load_ushort v125, v[66:67], off offset:128
	global_load_ushort v124, v[66:67], off offset:192
	v_mad_u32_u24 v66, v196, s33, v168
	v_mov_b32_e32 v67, v153
	v_lshl_add_u64 v[66:67], v[64:65], 0, v[66:67]
	global_load_ushort v123, v[66:67], off
	global_load_ushort v122, v[66:67], off offset:64
	global_load_ushort v121, v[66:67], off offset:128
	global_load_ushort v120, v[66:67], off offset:192
	v_mad_u32_u24 v66, v196, s33, v169
	v_mov_b32_e32 v67, v153
	v_lshl_add_u64 v[66:67], v[64:65], 0, v[66:67]
	v_pk_fma_f32 v[78:79], v[0:1], v[0:1], v[78:79]
	global_load_ushort v119, v[66:67], off
	global_load_ushort v118, v[66:67], off offset:64
	global_load_ushort v117, v[66:67], off offset:128
	global_load_ushort v116, v[66:67], off offset:192
	v_mad_u32_u24 v66, v196, s33, v170
	v_mov_b32_e32 v67, v153
	v_pk_fma_f32 v[78:79], v[32:33], v[32:33], v[78:79]
	v_lshl_add_u64 v[66:67], v[64:65], 0, v[66:67]
	v_pk_fma_f32 v[78:79], v[48:49], v[48:49], v[78:79]
	global_load_ushort v115, v[66:67], off
	global_load_ushort v114, v[66:67], off offset:64
	global_load_ushort v113, v[66:67], off offset:128
	global_load_ushort v112, v[66:67], off offset:192
	v_mad_u32_u24 v66, v196, s33, v171
	v_mov_b32_e32 v67, v153
	s_nop 1
	v_mov_b32_dpp v80, v78 quad_perm:[1,0,3,2] row_mask:0xf bank_mask:0xf
	s_nop 1
	v_mov_b32_dpp v81, v79 quad_perm:[1,0,3,2] row_mask:0xf bank_mask:0xf
	v_lshl_add_u64 v[66:67], v[64:65], 0, v[66:67]
	global_load_ushort v111, v[66:67], off
	global_load_ushort v110, v[66:67], off offset:64
	global_load_ushort v109, v[66:67], off offset:128
	global_load_ushort v108, v[66:67], off offset:192
	v_mad_u32_u24 v66, v196, s33, v172
	v_mov_b32_e32 v67, v153
	v_pk_mul_f32 v[72:73], v[26:27], v[26:27]
	v_lshl_add_u64 v[66:67], v[64:65], 0, v[66:67]
	v_pk_mul_f32 v[74:75], v[28:29], v[28:29]
	v_pk_fma_f32 v[72:73], v[10:11], v[10:11], v[72:73]
	global_load_ushort v107, v[66:67], off
	global_load_ushort v106, v[66:67], off offset:64
	global_load_ushort v105, v[66:67], off offset:128
	global_load_ushort v104, v[66:67], off offset:192
	v_mad_u32_u24 v66, v196, s33, v173
	v_mov_b32_e32 v67, v153
	v_pk_fma_f32 v[74:75], v[12:13], v[12:13], v[74:75]
	v_pk_fma_f32 v[72:73], v[42:43], v[42:43], v[72:73]
	v_lshl_add_u64 v[66:67], v[64:65], 0, v[66:67]
	v_pk_fma_f32 v[74:75], v[44:45], v[44:45], v[74:75]
	v_pk_fma_f32 v[82:83], v[58:59], v[58:59], v[72:73]
	s_waitcnt lgkmcnt(0)
; __device__ __forceinline__ void ret_block(const bf16_t* __restrict__ proj, const bf16_t* __restrict__ state, bf16_t* __restrict__ mixed, int b, int h, int qb, char* lds) {
;     ...
;     float ssr[16];
; #pragma unroll
;     for (int r = 0; r < 16; ++r) { float s = 0.f;
; #pragma unroll
;         for (int d0 = 0; d0 < 4; ++d0) s += o[d0][r] * o[d0][r];
;         s += __shfl_xor(s, 1); s += __shfl_xor(s, 2); s += __shfl_xor(s, 4); s += __shfl_xor(s, 8); s += __shfl_xor(s, 16);
;         ssr[r] = s; }
	v_pk_add_f32 v[72:73], v[78:79], v[80:81]
	global_load_ushort v103, v[66:67], off
	global_load_ushort v102, v[66:67], off offset:64
	global_load_ushort v101, v[66:67], off offset:128
	global_load_ushort v100, v[66:67], off offset:192
	v_mad_u32_u24 v66, v196, s33, v174
	v_mov_b32_e32 v67, v153
	v_pk_fma_f32 v[86:87], v[60:61], v[60:61], v[74:75]
	s_nop 1
	v_mov_b32_dpp v74, v72 quad_perm:[2,3,0,1] row_mask:0xf bank_mask:0xf
	s_nop 1
	v_mov_b32_dpp v75, v73 quad_perm:[2,3,0,1] row_mask:0xf bank_mask:0xf
	v_lshl_add_u64 v[64:65], v[64:65], 0, v[66:67]
	global_load_ushort v99, v[64:65], off
	global_load_ushort v98, v[64:65], off offset:64
	global_load_ushort v97, v[64:65], off offset:128
	global_load_ushort v96, v[64:65], off offset:192
	v_pk_mul_f32 v[64:65], v[18:19], v[18:19]
	v_pk_mul_f32 v[70:71], v[24:25], v[24:25]
	v_pk_mul_f32 v[76:77], v[30:31], v[30:31]
	v_pk_fma_f32 v[64:65], v[2:3], v[2:3], v[64:65]
	v_pk_fma_f32 v[76:77], v[14:15], v[14:15], v[76:77]
	v_pk_fma_f32 v[70:71], v[8:9], v[8:9], v[70:71]
	v_pk_fma_f32 v[64:65], v[34:35], v[34:35], v[64:65]
	v_pk_fma_f32 v[70:71], v[40:41], v[40:41], v[70:71]
	v_pk_fma_f32 v[76:77], v[46:47], v[46:47], v[76:77]
	v_pk_fma_f32 v[64:65], v[50:51], v[50:51], v[64:65]
	s_waitcnt lgkmcnt(0)
	v_pk_add_f32 v[72:73], v[72:73], v[74:75]
	v_pk_fma_f32 v[84:85], v[62:63], v[62:63], v[76:77]
	v_pk_fma_f32 v[76:77], v[56:57], v[56:57], v[70:71]
	s_nop 1
	v_mov_b32_dpp v70, v64 quad_perm:[1,0,3,2] row_mask:0xf bank_mask:0xf
	s_nop 1
	v_mov_b32_dpp v71, v65 quad_perm:[1,0,3,2] row_mask:0xf bank_mask:0xf
	s_nop 1
	v_mov_b32_dpp v74, v72 row_half_mirror row_mask:0xf bank_mask:0xf
	s_nop 1
	v_mov_b32_dpp v75, v73 row_half_mirror row_mask:0xf bank_mask:0xf
	v_pk_mul_f32 v[68:69], v[22:23], v[22:23]
	v_pk_mul_f32 v[66:67], v[20:21], v[20:21]
	v_pk_fma_f32 v[68:69], v[6:7], v[6:7], v[68:69]
	s_waitcnt lgkmcnt(0)
	v_pk_add_f32 v[64:65], v[64:65], v[70:71]
	v_pk_fma_f32 v[68:69], v[38:39], v[38:39], v[68:69]
	v_pk_add_f32 v[70:71], v[72:73], v[74:75]
	v_pk_fma_f32 v[78:79], v[54:55], v[54:55], v[68:69]
	s_nop 1
	v_mov_b32_dpp v68, v64 quad_perm:[2,3,0,1] row_mask:0xf bank_mask:0xf
	s_nop 1
	v_mov_b32_dpp v69, v65 quad_perm:[2,3,0,1] row_mask:0xf bank_mask:0xf
	s_nop 1
	v_mov_b32_dpp v72, v70 row_mirror row_mask:0xf bank_mask:0xf
	s_nop 1
	v_mov_b32_dpp v73, v71 row_mirror row_mask:0xf bank_mask:0xf
	v_pk_fma_f32 v[66:67], v[4:5], v[4:5], v[66:67]
	s_nop 1
	v_mov_b32_dpp v92, v82 quad_perm:[1,0,3,2] row_mask:0xf bank_mask:0xf
	v_pk_fma_f32 v[66:67], v[36:37], v[36:37], v[66:67]
	s_waitcnt lgkmcnt(0)
	v_pk_add_f32 v[68:69], v[64:65], v[68:69]
	v_pk_fma_f32 v[74:75], v[52:53], v[52:53], v[66:67]
	v_pk_add_f32 v[64:65], v[70:71], v[72:73]
	s_nop 1
	v_mov_b32_dpp v70, v74 quad_perm:[1,0,3,2] row_mask:0xf bank_mask:0xf
	s_nop 1
	v_mov_b32_dpp v71, v75 quad_perm:[1,0,3,2] row_mask:0xf bank_mask:0xf
	s_nop 1
	v_mov_b32_dpp v80, v68 row_half_mirror row_mask:0xf bank_mask:0xf
	s_nop 1
	v_mov_b32_dpp v81, v69 row_half_mirror row_mask:0xf bank_mask:0xf
	s_nop 1
	v_mov_b32_dpp v93, v83 quad_perm:[1,0,3,2] row_mask:0xf bank_mask:0xf
	s_nop 1
	v_mov_b32_dpp v94, v84 quad_perm:[1,0,3,2] row_mask:0xf bank_mask:0xf
	s_waitcnt lgkmcnt(0)
	v_pk_add_f32 v[70:71], v[74:75], v[70:71]
	s_nop 1
	v_mov_b32_dpp v74, v70 quad_perm:[2,3,0,1] row_mask:0xf bank_mask:0xf
	v_pk_add_f32 v[68:69], v[68:69], v[80:81]
	s_nop 1
	v_mov_b32_dpp v75, v71 quad_perm:[2,3,0,1] row_mask:0xf bank_mask:0xf
	s_nop 1
	v_mov_b32_dpp v72, v68 row_mirror row_mask:0xf bank_mask:0xf
	s_nop 1
	v_mov_b32_dpp v73, v69 row_mirror row_mask:0xf bank_mask:0xf
	v_pk_add_f32 v[82:83], v[82:83], v[92:93]
	s_nop 1
	v_mov_b32_dpp v95, v85 quad_perm:[1,0,3,2] row_mask:0xf bank_mask:0xf
	s_waitcnt lgkmcnt(0)
	v_pk_add_f32 v[74:75], v[70:71], v[74:75]
	s_nop 1
	v_mov_b32_dpp v80, v74 row_half_mirror row_mask:0xf bank_mask:0xf
	v_pk_add_f32 v[68:69], v[68:69], v[72:73]
	s_nop 1
	v_mov_b32_dpp v72, v78 quad_perm:[1,0,3,2] row_mask:0xf bank_mask:0xf
	s_nop 1
	v_mov_b32_dpp v73, v79 quad_perm:[1,0,3,2] row_mask:0xf bank_mask:0xf
	s_nop 1
	v_mov_b32_dpp v81, v75 row_half_mirror row_mask:0xf bank_mask:0xf
	v_pk_add_f32 v[94:95], v[84:85], v[94:95]
	s_nop 1
	v_mov_b32_dpp v202, v94 quad_perm:[2,3,0,1] row_mask:0xf bank_mask:0xf
	s_nop 1
	v_mov_b32_dpp v203, v95 quad_perm:[2,3,0,1] row_mask:0xf bank_mask:0xf
	s_waitcnt lgkmcnt(0)
	v_pk_add_f32 v[72:73], v[78:79], v[72:73]
	v_pk_add_f32 v[74:75], v[74:75], v[80:81]
	s_nop 1
	v_mov_b32_dpp v78, v72 quad_perm:[2,3,0,1] row_mask:0xf bank_mask:0xf
	s_nop 1
	v_mov_b32_dpp v79, v73 quad_perm:[2,3,0,1] row_mask:0xf bank_mask:0xf
	s_nop 1
	v_mov_b32_dpp v80, v74 row_mirror row_mask:0xf bank_mask:0xf
	s_nop 1
	v_mov_b32_dpp v81, v75 row_mirror row_mask:0xf bank_mask:0xf
	ds_bpermute_b32 v66, v160, v64
	ds_bpermute_b32 v67, v160, v65
	s_waitcnt lgkmcnt(0)
	v_pk_add_f32 v[78:79], v[72:73], v[78:79]
	s_nop 1
	v_mov_b32_dpp v88, v78 row_half_mirror row_mask:0xf bank_mask:0xf
	v_pk_add_f32 v[72:73], v[74:75], v[80:81]
	s_nop 1
	v_mov_b32_dpp v80, v76 quad_perm:[1,0,3,2] row_mask:0xf bank_mask:0xf
	s_nop 1
	v_mov_b32_dpp v81, v77 quad_perm:[1,0,3,2] row_mask:0xf bank_mask:0xf
	s_nop 1
	v_mov_b32_dpp v89, v79 row_half_mirror row_mask:0xf bank_mask:0xf
	ds_bpermute_b32 v70, v160, v68
	ds_bpermute_b32 v71, v160, v69
	ds_bpermute_b32 v74, v160, v72
	s_waitcnt lgkmcnt(0)
	v_pk_add_f32 v[80:81], v[76:77], v[80:81]
	v_pk_add_f32 v[78:79], v[78:79], v[88:89]
	s_nop 1
	v_mov_b32_dpp v90, v80 quad_perm:[2,3,0,1] row_mask:0xf bank_mask:0xf
	s_nop 1
	v_mov_b32_dpp v91, v81 quad_perm:[2,3,0,1] row_mask:0xf bank_mask:0xf
	s_nop 1
	v_mov_b32_dpp v88, v78 row_mirror row_mask:0xf bank_mask:0xf
	s_nop 1
	v_mov_b32_dpp v89, v79 row_mirror row_mask:0xf bank_mask:0xf
	ds_bpermute_b32 v75, v160, v73
	v_cmp_eq_u32_e32 vcc, 0, v194
	s_waitcnt lgkmcnt(0)
; __device__ __forceinline__ int crow(int r, int hi) { return (r & 3) + 8 * (r >> 2) + 4 * hi; }
; __device__ __forceinline__ unsigned cvtpk(float lo, float hi) { unsigned r; asm volatile("v_cvt_pk_bf16_f32 %0, %1, %2" : "=v"(r) : "v"(lo), "v"(hi)); return r; }
; __device__ __forceinline__ float bf2f(bf16_t v) { return __uint_as_float(((unsigned)v) << 16); }
; __device__ __forceinline__ void ret_block(const bf16_t* __restrict__ proj, const bf16_t* __restrict__ state, bf16_t* __restrict__ mixed, int b, int h, int qb, char* lds) {
;     ...
;     float ssr[16];
; #pragma unroll
;     for (int r = 0; r < 16; ++r) { float s = 0.f;
; #pragma unroll
;         for (int d0 = 0; d0 < 4; ++d0) s += o[d0][r] * o[d0][r];
;         s += __shfl_xor(s, 1); s += __shfl_xor(s, 2); s += __shfl_xor(s, 4); s += __shfl_xor(s, 8); s += __shfl_xor(s, 16);
;         ssr[r] = s; }
;     if (r32 == 0) {
; #pragma unroll
;         for (int r = 0; r < 16; ++r) ssx[e * 128 + wq * 32 + crow(r, hi)] = ssr[r]; }
;     __syncthreads();
; #pragma unroll
;     for (int r = 0; r < 16; ++r) { const int orow = crow(r, hi); const float tot = ssx[wq * 32 + orow] + ssx[128 + wq * 32 + orow];
;         const float rs = __builtin_amdgcn_rsqf(tot * (1.0f / 256.0f) + 1e-6f);
; #pragma unroll
;         for (int d0 = 0; d0 < 4; ++d0) { const float g = bf2f(graw[r][d0]);
;             const float v = o[d0][r] * rs * g * __builtin_amdgcn_rcpf(1.0f + __builtin_amdgcn_exp2f(-LOG2E * g)); const float vn = __shfl_xor(v, 1);
;             if ((r32 & 1) == 0) *(unsigned*)(Op + (size_t)orow * LDO + d0 * 32 + r32) = cvtpk(v, vn); } }
	v_pk_add_f32 v[80:81], v[80:81], v[90:91]
	s_nop 1
	v_mov_b32_dpp v90, v82 quad_perm:[2,3,0,1] row_mask:0xf bank_mask:0xf
	v_pk_add_f32 v[76:77], v[78:79], v[88:89]
	s_nop 1
	v_mov_b32_dpp v88, v80 row_half_mirror row_mask:0xf bank_mask:0xf
	s_nop 1
	v_mov_b32_dpp v89, v81 row_half_mirror row_mask:0xf bank_mask:0xf
	s_nop 1
	v_mov_b32_dpp v91, v83 quad_perm:[2,3,0,1] row_mask:0xf bank_mask:0xf
	ds_bpermute_b32 v78, v160, v76
	ds_bpermute_b32 v79, v160, v77
	s_waitcnt lgkmcnt(0)
	v_pk_add_f32 v[80:81], v[80:81], v[88:89]
	v_pk_add_f32 v[90:91], v[82:83], v[90:91]
	s_nop 1
	v_mov_b32_dpp v88, v80 row_mirror row_mask:0xf bank_mask:0xf
	s_nop 1
	v_mov_b32_dpp v89, v81 row_mirror row_mask:0xf bank_mask:0xf
	s_nop 1
	v_mov_b32_dpp v92, v90 row_half_mirror row_mask:0xf bank_mask:0xf
	s_nop 1
	v_mov_b32_dpp v93, v91 row_half_mirror row_mask:0xf bank_mask:0xf
	s_waitcnt lgkmcnt(0)
	v_pk_add_f32 v[80:81], v[80:81], v[88:89]
	ds_bpermute_b32 v82, v160, v80
	v_pk_add_f32 v[88:89], v[90:91], v[92:93]
	s_nop 1
	v_mov_b32_dpp v90, v86 quad_perm:[1,0,3,2] row_mask:0xf bank_mask:0xf
	s_nop 1
	v_mov_b32_dpp v91, v87 quad_perm:[1,0,3,2] row_mask:0xf bank_mask:0xf
	s_nop 1
	v_mov_b32_dpp v92, v88 row_mirror row_mask:0xf bank_mask:0xf
	s_nop 1
	v_mov_b32_dpp v93, v89 row_mirror row_mask:0xf bank_mask:0xf
	ds_bpermute_b32 v83, v160, v81
	s_waitcnt lgkmcnt(0)
	v_pk_add_f32 v[86:87], v[86:87], v[90:91]
	s_nop 1
	v_mov_b32_dpp v90, v86 quad_perm:[2,3,0,1] row_mask:0xf bank_mask:0xf
	s_nop 1
	v_mov_b32_dpp v91, v87 quad_perm:[2,3,0,1] row_mask:0xf bank_mask:0xf
	v_pk_add_f32 v[84:85], v[88:89], v[92:93]
	v_pk_add_f32 v[92:93], v[94:95], v[202:203]
	s_nop 1
	v_mov_b32_dpp v94, v92 row_half_mirror row_mask:0xf bank_mask:0xf
	s_nop 1
	v_mov_b32_dpp v95, v93 row_half_mirror row_mask:0xf bank_mask:0xf
	s_waitcnt lgkmcnt(0)
	v_pk_add_f32 v[88:89], v[86:87], v[90:91]
	s_nop 1
	v_mov_b32_dpp v90, v88 row_half_mirror row_mask:0xf bank_mask:0xf
	s_nop 1
	v_mov_b32_dpp v91, v89 row_half_mirror row_mask:0xf bank_mask:0xf
	ds_bpermute_b32 v86, v160, v84
	v_pk_add_f32 v[92:93], v[92:93], v[94:95]
	s_nop 1
	v_mov_b32_dpp v94, v92 row_mirror row_mask:0xf bank_mask:0xf
	s_nop 1
	v_mov_b32_dpp v95, v93 row_mirror row_mask:0xf bank_mask:0xf
	s_waitcnt lgkmcnt(0)
	v_pk_add_f32 v[88:89], v[88:89], v[90:91]
	s_nop 1
	v_mov_b32_dpp v90, v88 row_mirror row_mask:0xf bank_mask:0xf
	s_nop 1
	v_mov_b32_dpp v91, v89 row_mirror row_mask:0xf bank_mask:0xf
	ds_bpermute_b32 v87, v160, v85
	v_pk_add_f32 v[92:93], v[92:93], v[94:95]
	ds_bpermute_b32 v94, v160, v92
	ds_bpermute_b32 v95, v160, v93
	s_waitcnt lgkmcnt(0)
	v_pk_add_f32 v[88:89], v[88:89], v[90:91]
	ds_bpermute_b32 v90, v160, v88
	ds_bpermute_b32 v91, v160, v89
	s_and_saveexec_b64 s[6:7], vcc
	s_cbranch_execz .LBB0_488
	s_lshl_b32 s5, s51, 2
	s_add_i32 s5, s5, 0
	s_lshl_b32 s4, s4, 2
	s_add_i32 s5, s5, s4
	v_lshl_add_u32 v194, v191, 2, s5
	v_add_u32_e32 v194, 0x20000, v194
	v_pk_add_f32 v[64:65], v[64:65], v[66:67]
	v_pk_add_f32 v[66:67], v[68:69], v[70:71]
	ds_write_b128 v194, v[64:67]
	v_pk_add_f32 v[64:65], v[72:73], v[74:75]
	v_pk_add_f32 v[66:67], v[76:77], v[78:79]
	ds_write_b128 v194, v[64:67] offset:32
	v_pk_add_f32 v[64:65], v[80:81], v[82:83]
	v_pk_add_f32 v[66:67], v[84:85], v[86:87]
	ds_write_b128 v194, v[64:67] offset:64
	s_waitcnt lgkmcnt(0)
	v_pk_add_f32 v[64:65], v[88:89], v[90:91]
	v_pk_add_f32 v[66:67], v[92:93], v[94:95]
	ds_write_b128 v194, v[64:67] offset:96
.LBB0_488:
	s_or_b64 exec, exec, s[6:7]
	s_or_b32 s4, s51, s50
	s_ashr_i32 s5, s4, 31
	s_lshl_b64 s[4:5], s[4:5], 12
	s_add_u32 s4, s47, s4
	s_addc_u32 s5, s48, s5
	s_add_u32 s0, s4, s0
	s_addc_u32 s1, s5, s1
	s_lshl_b32 s4, s51, 2
	s_add_i32 s4, s4, 0
	v_lshl_add_u32 v64, v191, 2, s4
	v_add_u32_e32 v68, 0x20000, v64
	s_waitcnt vmcnt(0) lgkmcnt(0)
	s_barrier
	ds_read2st64_b32 v[64:65], v68 offset1:2
	v_lshlrev_b32_e32 v66, 16, v201
	v_mul_f32_e32 v67, 0xbfb8aa3b, v66
	v_exp_f32_e32 v67, v67
	s_waitcnt lgkmcnt(0)
	v_add_f32_e32 v64, v64, v65
	v_fmamk_f32 v64, v64, 0x3b800000, v161
	v_rsq_f32_e32 v69, v64
	v_add_f32_e32 v64, 1.0, v67
	v_rcp_f32_e32 v64, v64
	v_and_b32_e32 v65, 1, v193
	v_mul_f32_e32 v0, v0, v69
	v_mul_f32_e32 v0, v0, v66
	v_mul_f32_e32 v0, v64, v0
	s_nop 1
	v_mov_b32_dpp v70, v0 quad_perm:[1,0,3,2] row_mask:0xf bank_mask:0xf
	v_cmp_eq_u32_e32 vcc, 0, v65
	v_lshl_add_u64 v[64:65], s[0:1], 0, v[152:153]
	v_lshlrev_b32_e32 v152, 14, v192
	v_lshl_add_u64 v[66:67], v[64:65], 0, v[152:153]
	s_and_saveexec_b64 s[0:1], vcc
	s_cbranch_execz .LBB0_490
	s_waitcnt lgkmcnt(0)
	v_cvt_pk_bf16_f32 v0, v0, v70
	global_store_dword v[66:67], v0, off offset:2048
.LBB0_490:
	s_or_b64 exec, exec, s[0:1]
	v_lshlrev_b32_e32 v0, 16, v200
	s_waitcnt lgkmcnt(0)
	v_mul_f32_e32 v70, 0xbfb8aa3b, v0
	v_exp_f32_e32 v70, v70
	v_mul_f32_e32 v16, v16, v69
	v_mul_f32_e32 v0, v16, v0
	v_add_f32_e32 v70, 1.0, v70
	v_rcp_f32_e32 v70, v70
	s_nop 0
	v_mul_f32_e32 v0, v70, v0
	s_nop 1
	v_mov_b32_dpp v16, v0 quad_perm:[1,0,3,2] row_mask:0xf bank_mask:0xf
	s_and_saveexec_b64 s[0:1], vcc
	s_cbranch_execz .LBB0_492
	s_waitcnt lgkmcnt(0)
	v_cvt_pk_bf16_f32 v0, v0, v16
	global_store_dword v[66:67], v0, off offset:2112
.LBB0_492:
	s_or_b64 exec, exec, s[0:1]
	v_lshlrev_b32_e32 v0, 16, v199
	s_waitcnt lgkmcnt(0)
	v_mul_f32_e32 v16, 0xbfb8aa3b, v0
	v_exp_f32_e32 v16, v16
	v_mul_f32_e32 v32, v32, v69
	v_mul_f32_e32 v0, v32, v0
	v_add_f32_e32 v16, 1.0, v16
	v_rcp_f32_e32 v16, v16
	s_nop 0
	v_mul_f32_e32 v0, v16, v0
	s_nop 1
	v_mov_b32_dpp v16, v0 quad_perm:[1,0,3,2] row_mask:0xf bank_mask:0xf
	s_and_saveexec_b64 s[0:1], vcc
	s_cbranch_execz .LBB0_494
	s_waitcnt lgkmcnt(0)
	v_cvt_pk_bf16_f32 v0, v0, v16
	global_store_dword v[66:67], v0, off offset:2176
; __device__ __forceinline__ int crow(int r, int hi) { return (r & 3) + 8 * (r >> 2) + 4 * hi; }
; __device__ __forceinline__ unsigned cvtpk(float lo, float hi) { unsigned r; asm volatile("v_cvt_pk_bf16_f32 %0, %1, %2" : "=v"(r) : "v"(lo), "v"(hi)); return r; }
; __device__ __forceinline__ float bf2f(bf16_t v) { return __uint_as_float(((unsigned)v) << 16); }
; __device__ __forceinline__ void ret_block(const bf16_t* __restrict__ proj, const bf16_t* __restrict__ state, bf16_t* __restrict__ mixed, int b, int h, int qb, char* lds) {
;     ...
; #pragma unroll
;     for (int r = 0; r < 16; ++r) { const int orow = crow(r, hi); const float tot = ssx[wq * 32 + orow] + ssx[128 + wq * 32 + orow];
;         const float rs = __builtin_amdgcn_rsqf(tot * (1.0f / 256.0f) + 1e-6f);
; #pragma unroll
;         for (int d0 = 0; d0 < 4; ++d0) { const float g = bf2f(graw[r][d0]);
;             const float v = o[d0][r] * rs * g * __builtin_amdgcn_rcpf(1.0f + __builtin_amdgcn_exp2f(-LOG2E * g)); const float vn = __shfl_xor(v, 1);
;             if ((r32 & 1) == 0) *(unsigned*)(Op + (size_t)orow * LDO + d0 * 32 + r32) = cvtpk(v, vn); } }
.LBB0_494:
	s_or_b64 exec, exec, s[0:1]
	v_lshlrev_b32_e32 v0, 16, v198
	s_waitcnt lgkmcnt(0)
	v_mul_f32_e32 v16, 0xbfb8aa3b, v0
	v_exp_f32_e32 v16, v16
	v_mul_f32_e32 v32, v48, v69
	v_mul_f32_e32 v0, v32, v0
	v_add_f32_e32 v16, 1.0, v16
	v_rcp_f32_e32 v16, v16
	s_nop 0
	v_mul_f32_e32 v0, v16, v0
	s_nop 1
	v_mov_b32_dpp v16, v0 quad_perm:[1,0,3,2] row_mask:0xf bank_mask:0xf
	s_and_saveexec_b64 s[0:1], vcc
	s_cbranch_execz .LBB0_496
	s_waitcnt lgkmcnt(0)
	v_cvt_pk_bf16_f32 v0, v0, v16
	global_store_dword v[66:67], v0, off offset:2240
.LBB0_496:
	s_or_b64 exec, exec, s[0:1]
	ds_read2_b32 v[66:67], v68 offset0:1 offset1:129
	v_lshlrev_b32_e32 v0, 16, v197
	s_waitcnt lgkmcnt(1)
	v_mul_f32_e32 v16, 0xbfb8aa3b, v0
	v_exp_f32_e32 v32, v16
	v_lshlrev_b32_e32 v152, 12, v196
	s_waitcnt lgkmcnt(0)
	v_add_f32_e32 v16, v66, v67
	v_fmamk_f32 v16, v16, 0x3b800000, v161
	v_rsq_f32_e32 v16, v16
	v_add_f32_e32 v32, 1.0, v32
	v_rcp_f32_e32 v32, v32
	v_mul_f32_e32 v1, v1, v16
	v_mul_f32_e32 v0, v1, v0
	v_mul_f32_e32 v32, v32, v0
	s_nop 1
	v_mov_b32_dpp v48, v32 quad_perm:[1,0,3,2] row_mask:0xf bank_mask:0xf
	v_lshl_add_u64 v[0:1], v[64:65], 0, v[152:153]
	s_and_saveexec_b64 s[0:1], vcc
	s_cbranch_execz .LBB0_498
	s_waitcnt lgkmcnt(0)
	v_cvt_pk_bf16_f32 v32, v32, v48
	global_store_dword v[0:1], v32, off offset:2048
.LBB0_498:
	s_or_b64 exec, exec, s[0:1]
	v_lshlrev_b32_e32 v32, 16, v195
	s_waitcnt lgkmcnt(0)
	v_mul_f32_e32 v48, 0xbfb8aa3b, v32
	v_exp_f32_e32 v48, v48
	v_mul_f32_e32 v17, v17, v16
	v_mul_f32_e32 v17, v17, v32
	v_add_f32_e32 v48, 1.0, v48
	v_rcp_f32_e32 v48, v48
	s_nop 0
	v_mul_f32_e32 v17, v48, v17
	s_nop 1
	v_mov_b32_dpp v32, v17 quad_perm:[1,0,3,2] row_mask:0xf bank_mask:0xf
	s_and_saveexec_b64 s[0:1], vcc
	s_cbranch_execz .LBB0_500
	s_waitcnt lgkmcnt(0)
	v_cvt_pk_bf16_f32 v17, v17, v32
	global_store_dword v[0:1], v17, off offset:2112
.LBB0_500:
	s_or_b64 exec, exec, s[0:1]
	v_lshlrev_b32_e32 v17, 16, v155
	s_waitcnt lgkmcnt(0)
	v_mul_f32_e32 v32, 0xbfb8aa3b, v17
	v_exp_f32_e32 v32, v32
	v_mul_f32_e32 v33, v33, v16
	v_mul_f32_e32 v17, v33, v17
	v_add_f32_e32 v32, 1.0, v32
	v_rcp_f32_e32 v32, v32
	s_nop 0
	v_mul_f32_e32 v17, v32, v17
	s_nop 1
	v_mov_b32_dpp v32, v17 quad_perm:[1,0,3,2] row_mask:0xf bank_mask:0xf
	s_and_saveexec_b64 s[0:1], vcc
	s_cbranch_execz .LBB0_502
	s_waitcnt lgkmcnt(0)
	v_cvt_pk_bf16_f32 v17, v17, v32
	global_store_dword v[0:1], v17, off offset:2176
.LBB0_502:
	s_or_b64 exec, exec, s[0:1]
	v_lshlrev_b32_e32 v17, 16, v154
	s_waitcnt lgkmcnt(0)
	v_mul_f32_e32 v32, 0xbfb8aa3b, v17
	v_exp_f32_e32 v32, v32
	v_mul_f32_e32 v16, v49, v16
	v_mul_f32_e32 v16, v16, v17
	v_add_f32_e32 v32, 1.0, v32
	v_rcp_f32_e32 v32, v32
	s_nop 0
	v_mul_f32_e32 v16, v32, v16
	s_nop 1
	v_mov_b32_dpp v17, v16 quad_perm:[1,0,3,2] row_mask:0xf bank_mask:0xf
	s_and_saveexec_b64 s[0:1], vcc
	s_cbranch_execz .LBB0_504
	s_waitcnt lgkmcnt(0)
	v_cvt_pk_bf16_f32 v16, v16, v17
	global_store_dword v[0:1], v16, off offset:2240
.LBB0_504:
	s_or_b64 exec, exec, s[0:1]
	ds_read2_b32 v[0:1], v68 offset0:2 offset1:130
	s_waitcnt lgkmcnt(1)
	v_lshlrev_b32_e32 v17, 16, v151
	v_mul_f32_e32 v16, 0xbfb8aa3b, v17
	v_exp_f32_e32 v32, v16
	v_lshl_or_b32 v152, v191, 12, v175
	s_waitcnt lgkmcnt(0)
	v_add_f32_e32 v0, v0, v1
	v_fmamk_f32 v0, v0, 0x3b800000, v161
	v_rsq_f32_e32 v16, v0
	v_add_f32_e32 v0, 1.0, v32
	v_rcp_f32_e32 v0, v0
	v_mul_f32_e32 v1, v2, v16
	v_mul_f32_e32 v1, v1, v17
	v_mul_f32_e32 v2, v0, v1
	s_nop 1
	v_mov_b32_dpp v17, v2 quad_perm:[1,0,3,2] row_mask:0xf bank_mask:0xf
	v_lshl_add_u64 v[0:1], v[64:65], 0, v[152:153]
	s_and_saveexec_b64 s[0:1], vcc
	s_cbranch_execz .LBB0_506
	s_waitcnt lgkmcnt(0)
	v_cvt_pk_bf16_f32 v2, v2, v17
	global_store_dword v[0:1], v2, off offset:2048
.LBB0_506:
	s_or_b64 exec, exec, s[0:1]
	v_lshlrev_b32_e32 v2, 16, v150
	s_waitcnt lgkmcnt(0)
	v_mul_f32_e32 v17, 0xbfb8aa3b, v2
	v_exp_f32_e32 v17, v17
	v_mul_f32_e32 v18, v18, v16
	v_mul_f32_e32 v2, v18, v2
	v_add_f32_e32 v17, 1.0, v17
	v_rcp_f32_e32 v17, v17
	s_nop 0
	v_mul_f32_e32 v2, v17, v2
	s_nop 1
	v_mov_b32_dpp v17, v2 quad_perm:[1,0,3,2] row_mask:0xf bank_mask:0xf
	s_and_saveexec_b64 s[0:1], vcc
	s_cbranch_execz .LBB0_508
	s_waitcnt lgkmcnt(0)
	v_cvt_pk_bf16_f32 v2, v2, v17
	global_store_dword v[0:1], v2, off offset:2112
.LBB0_508:
	s_or_b64 exec, exec, s[0:1]
	v_lshlrev_b32_e32 v2, 16, v149
	s_waitcnt lgkmcnt(0)
	v_mul_f32_e32 v17, 0xbfb8aa3b, v2
	v_exp_f32_e32 v17, v17
	v_mul_f32_e32 v18, v34, v16
	v_mul_f32_e32 v2, v18, v2
	v_add_f32_e32 v17, 1.0, v17
	v_rcp_f32_e32 v17, v17
	s_nop 0
	v_mul_f32_e32 v2, v17, v2
	s_nop 1
	v_mov_b32_dpp v17, v2 quad_perm:[1,0,3,2] row_mask:0xf bank_mask:0xf
	s_and_saveexec_b64 s[0:1], vcc
	s_cbranch_execz .LBB0_510
	s_waitcnt lgkmcnt(0)
	v_cvt_pk_bf16_f32 v2, v2, v17
	global_store_dword v[0:1], v2, off offset:2176
.LBB0_510:
	s_or_b64 exec, exec, s[0:1]
	v_lshlrev_b32_e32 v2, 16, v148
	s_waitcnt lgkmcnt(0)
	v_mul_f32_e32 v17, 0xbfb8aa3b, v2
	v_exp_f32_e32 v17, v17
	v_mul_f32_e32 v16, v50, v16
	v_mul_f32_e32 v2, v16, v2
	v_add_f32_e32 v17, 1.0, v17
	v_rcp_f32_e32 v17, v17
	s_nop 0
	v_mul_f32_e32 v2, v17, v2
	s_nop 1
	v_mov_b32_dpp v16, v2 quad_perm:[1,0,3,2] row_mask:0xf bank_mask:0xf
	s_and_saveexec_b64 s[0:1], vcc
	s_cbranch_execz .LBB0_512
	s_waitcnt lgkmcnt(0)
	v_cvt_pk_bf16_f32 v2, v2, v16
	global_store_dword v[0:1], v2, off offset:2240
; __device__ __forceinline__ int crow(int r, int hi) { return (r & 3) + 8 * (r >> 2) + 4 * hi; }
; __device__ __forceinline__ unsigned cvtpk(float lo, float hi) { unsigned r; asm volatile("v_cvt_pk_bf16_f32 %0, %1, %2" : "=v"(r) : "v"(lo), "v"(hi)); return r; }
; __device__ __forceinline__ float bf2f(bf16_t v) { return __uint_as_float(((unsigned)v) << 16); }
; __device__ __forceinline__ void ret_block(const bf16_t* __restrict__ proj, const bf16_t* __restrict__ state, bf16_t* __restrict__ mixed, int b, int h, int qb, char* lds) {
;     ...
; #pragma unroll
;     for (int r = 0; r < 16; ++r) { const int orow = crow(r, hi); const float tot = ssx[wq * 32 + orow] + ssx[128 + wq * 32 + orow];
;         const float rs = __builtin_amdgcn_rsqf(tot * (1.0f / 256.0f) + 1e-6f);
; #pragma unroll
;         for (int d0 = 0; d0 < 4; ++d0) { const float g = bf2f(graw[r][d0]);
;             const float v = o[d0][r] * rs * g * __builtin_amdgcn_rcpf(1.0f + __builtin_amdgcn_exp2f(-LOG2E * g)); const float vn = __shfl_xor(v, 1);
;             if ((r32 & 1) == 0) *(unsigned*)(Op + (size_t)orow * LDO + d0 * 32 + r32) = cvtpk(v, vn); } }
.LBB0_512:
	s_or_b64 exec, exec, s[0:1]
	ds_read2_b32 v[0:1], v68 offset0:3 offset1:131
	s_waitcnt lgkmcnt(1)
	v_lshlrev_b32_e32 v16, 16, v147
	v_mul_f32_e32 v2, 0xbfb8aa3b, v16
	v_exp_f32_e32 v17, v2
	v_lshl_or_b32 v152, v191, 12, v176
	s_waitcnt lgkmcnt(0)
	v_add_f32_e32 v0, v0, v1
	v_fmamk_f32 v0, v0, 0x3b800000, v161
	v_rsq_f32_e32 v2, v0
	v_add_f32_e32 v0, 1.0, v17
	v_rcp_f32_e32 v0, v0
	v_mul_f32_e32 v1, v3, v2
	v_mul_f32_e32 v1, v1, v16
	v_mul_f32_e32 v3, v0, v1
	s_nop 1
	v_mov_b32_dpp v16, v3 quad_perm:[1,0,3,2] row_mask:0xf bank_mask:0xf
	v_lshl_add_u64 v[0:1], v[64:65], 0, v[152:153]
	s_and_saveexec_b64 s[0:1], vcc
	s_cbranch_execz .LBB0_514
	s_waitcnt lgkmcnt(0)
	v_cvt_pk_bf16_f32 v3, v3, v16
	global_store_dword v[0:1], v3, off offset:2048
.LBB0_514:
	s_or_b64 exec, exec, s[0:1]
	v_lshlrev_b32_e32 v3, 16, v146
	s_waitcnt lgkmcnt(0)
	v_mul_f32_e32 v16, 0xbfb8aa3b, v3
	v_exp_f32_e32 v16, v16
	v_mul_f32_e32 v17, v19, v2
	v_mul_f32_e32 v3, v17, v3
	v_add_f32_e32 v16, 1.0, v16
	v_rcp_f32_e32 v16, v16
	s_nop 0
	v_mul_f32_e32 v3, v16, v3
	s_nop 1
	v_mov_b32_dpp v16, v3 quad_perm:[1,0,3,2] row_mask:0xf bank_mask:0xf
	s_and_saveexec_b64 s[0:1], vcc
	s_cbranch_execz .LBB0_516
	s_waitcnt lgkmcnt(0)
	v_cvt_pk_bf16_f32 v3, v3, v16
	global_store_dword v[0:1], v3, off offset:2112
.LBB0_516:
	s_or_b64 exec, exec, s[0:1]
	v_lshlrev_b32_e32 v3, 16, v145
	s_waitcnt lgkmcnt(0)
	v_mul_f32_e32 v16, 0xbfb8aa3b, v3
	v_exp_f32_e32 v16, v16
	v_mul_f32_e32 v17, v35, v2
	v_mul_f32_e32 v3, v17, v3
	v_add_f32_e32 v16, 1.0, v16
	v_rcp_f32_e32 v16, v16
	s_nop 0
	v_mul_f32_e32 v3, v16, v3
	s_nop 1
	v_mov_b32_dpp v16, v3 quad_perm:[1,0,3,2] row_mask:0xf bank_mask:0xf
	s_and_saveexec_b64 s[0:1], vcc
	s_cbranch_execz .LBB0_518
	s_waitcnt lgkmcnt(0)
	v_cvt_pk_bf16_f32 v3, v3, v16
	global_store_dword v[0:1], v3, off offset:2176
.LBB0_518:
	s_or_b64 exec, exec, s[0:1]
	v_lshlrev_b32_e32 v3, 16, v144
	s_waitcnt lgkmcnt(0)
	v_mul_f32_e32 v16, 0xbfb8aa3b, v3
	v_exp_f32_e32 v16, v16
	v_mul_f32_e32 v2, v51, v2
	v_mul_f32_e32 v2, v2, v3
	v_add_f32_e32 v16, 1.0, v16
	v_rcp_f32_e32 v16, v16
	s_nop 0
	v_mul_f32_e32 v2, v16, v2
	s_nop 1
	v_mov_b32_dpp v3, v2 quad_perm:[1,0,3,2] row_mask:0xf bank_mask:0xf
	s_and_saveexec_b64 s[0:1], vcc
	s_cbranch_execz .LBB0_520
	s_waitcnt lgkmcnt(0)
	v_cvt_pk_bf16_f32 v2, v2, v3
	global_store_dword v[0:1], v2, off offset:2240
.LBB0_520:
	s_or_b64 exec, exec, s[0:1]
	ds_read2_b32 v[0:1], v68 offset0:8 offset1:136
	s_waitcnt lgkmcnt(1)
	v_lshlrev_b32_e32 v3, 16, v143
	v_mul_f32_e32 v2, 0xbfb8aa3b, v3
	v_exp_f32_e32 v16, v2
	v_lshl_or_b32 v152, v191, 12, v177
	s_waitcnt lgkmcnt(0)
	v_add_f32_e32 v0, v0, v1
	v_fmamk_f32 v0, v0, 0x3b800000, v161
	v_rsq_f32_e32 v2, v0
	v_add_f32_e32 v0, 1.0, v16
	v_rcp_f32_e32 v0, v0
	v_mul_f32_e32 v1, v4, v2
	v_mul_f32_e32 v1, v1, v3
	v_mul_f32_e32 v3, v0, v1
	s_nop 1
	v_mov_b32_dpp v4, v3 quad_perm:[1,0,3,2] row_mask:0xf bank_mask:0xf
	v_lshl_add_u64 v[0:1], v[64:65], 0, v[152:153]
	s_and_saveexec_b64 s[0:1], vcc
	s_cbranch_execz .LBB0_522
	s_waitcnt lgkmcnt(0)
	v_cvt_pk_bf16_f32 v3, v3, v4
	global_store_dword v[0:1], v3, off offset:2048
.LBB0_522:
	s_or_b64 exec, exec, s[0:1]
	v_lshlrev_b32_e32 v3, 16, v142
	s_waitcnt lgkmcnt(0)
	v_mul_f32_e32 v4, 0xbfb8aa3b, v3
	v_exp_f32_e32 v4, v4
	v_mul_f32_e32 v16, v20, v2
	v_mul_f32_e32 v3, v16, v3
	v_add_f32_e32 v4, 1.0, v4
	v_rcp_f32_e32 v4, v4
	s_nop 0
	v_mul_f32_e32 v3, v4, v3
	s_nop 1
	v_mov_b32_dpp v4, v3 quad_perm:[1,0,3,2] row_mask:0xf bank_mask:0xf
	s_and_saveexec_b64 s[0:1], vcc
	s_cbranch_execz .LBB0_524
	s_waitcnt lgkmcnt(0)
	v_cvt_pk_bf16_f32 v3, v3, v4
	global_store_dword v[0:1], v3, off offset:2112
.LBB0_524:
	s_or_b64 exec, exec, s[0:1]
	v_lshlrev_b32_e32 v3, 16, v141
	s_waitcnt lgkmcnt(0)
	v_mul_f32_e32 v4, 0xbfb8aa3b, v3
	v_exp_f32_e32 v4, v4
	v_mul_f32_e32 v16, v36, v2
	v_mul_f32_e32 v3, v16, v3
	v_add_f32_e32 v4, 1.0, v4
	v_rcp_f32_e32 v4, v4
	s_nop 0
	v_mul_f32_e32 v3, v4, v3
	s_nop 1
	v_mov_b32_dpp v4, v3 quad_perm:[1,0,3,2] row_mask:0xf bank_mask:0xf
	s_and_saveexec_b64 s[0:1], vcc
	s_cbranch_execz .LBB0_526
	s_waitcnt lgkmcnt(0)
	v_cvt_pk_bf16_f32 v3, v3, v4
	global_store_dword v[0:1], v3, off offset:2176
.LBB0_526:
	s_or_b64 exec, exec, s[0:1]
	v_lshlrev_b32_e32 v3, 16, v140
	s_waitcnt lgkmcnt(0)
	v_mul_f32_e32 v4, 0xbfb8aa3b, v3
	v_exp_f32_e32 v4, v4
	v_mul_f32_e32 v2, v52, v2
	v_mul_f32_e32 v2, v2, v3
	v_add_f32_e32 v4, 1.0, v4
	v_rcp_f32_e32 v4, v4
	s_nop 0
	v_mul_f32_e32 v2, v4, v2
	s_nop 1
	v_mov_b32_dpp v3, v2 quad_perm:[1,0,3,2] row_mask:0xf bank_mask:0xf
	s_and_saveexec_b64 s[0:1], vcc
	s_cbranch_execz .LBB0_528
	s_waitcnt lgkmcnt(0)
	v_cvt_pk_bf16_f32 v2, v2, v3
	global_store_dword v[0:1], v2, off offset:2240
.LBB0_528:
	s_or_b64 exec, exec, s[0:1]
	ds_read2_b32 v[0:1], v68 offset0:9 offset1:137
	s_waitcnt lgkmcnt(1)
	v_lshlrev_b32_e32 v3, 16, v139
	v_mul_f32_e32 v2, 0xbfb8aa3b, v3
	v_exp_f32_e32 v4, v2
	v_lshl_or_b32 v152, v191, 12, v178
	s_waitcnt lgkmcnt(0)
	v_add_f32_e32 v0, v0, v1
	v_fmamk_f32 v0, v0, 0x3b800000, v161
	v_rsq_f32_e32 v2, v0
	v_add_f32_e32 v0, 1.0, v4
	v_rcp_f32_e32 v0, v0
	v_mul_f32_e32 v1, v5, v2
	v_mul_f32_e32 v1, v1, v3
	v_mul_f32_e32 v3, v0, v1
	s_nop 1
	v_mov_b32_dpp v4, v3 quad_perm:[1,0,3,2] row_mask:0xf bank_mask:0xf
	v_lshl_add_u64 v[0:1], v[64:65], 0, v[152:153]
	s_and_saveexec_b64 s[0:1], vcc
	s_cbranch_execz .LBB0_530
	s_waitcnt lgkmcnt(0)
	v_cvt_pk_bf16_f32 v3, v3, v4
	global_store_dword v[0:1], v3, off offset:2048
; __device__ __forceinline__ int crow(int r, int hi) { return (r & 3) + 8 * (r >> 2) + 4 * hi; }
; __device__ __forceinline__ unsigned cvtpk(float lo, float hi) { unsigned r; asm volatile("v_cvt_pk_bf16_f32 %0, %1, %2" : "=v"(r) : "v"(lo), "v"(hi)); return r; }
; __device__ __forceinline__ float bf2f(bf16_t v) { return __uint_as_float(((unsigned)v) << 16); }
; __device__ __forceinline__ void ret_block(const bf16_t* __restrict__ proj, const bf16_t* __restrict__ state, bf16_t* __restrict__ mixed, int b, int h, int qb, char* lds) {
;     ...
; #pragma unroll
;     for (int r = 0; r < 16; ++r) { const int orow = crow(r, hi); const float tot = ssx[wq * 32 + orow] + ssx[128 + wq * 32 + orow];
;         const float rs = __builtin_amdgcn_rsqf(tot * (1.0f / 256.0f) + 1e-6f);
; #pragma unroll
;         for (int d0 = 0; d0 < 4; ++d0) { const float g = bf2f(graw[r][d0]);
;             const float v = o[d0][r] * rs * g * __builtin_amdgcn_rcpf(1.0f + __builtin_amdgcn_exp2f(-LOG2E * g)); const float vn = __shfl_xor(v, 1);
;             if ((r32 & 1) == 0) *(unsigned*)(Op + (size_t)orow * LDO + d0 * 32 + r32) = cvtpk(v, vn); } }
.LBB0_530:
	s_or_b64 exec, exec, s[0:1]
	v_lshlrev_b32_e32 v3, 16, v138
	s_waitcnt lgkmcnt(0)
	v_mul_f32_e32 v4, 0xbfb8aa3b, v3
	v_exp_f32_e32 v4, v4
	v_mul_f32_e32 v5, v21, v2
	v_mul_f32_e32 v3, v5, v3
	v_add_f32_e32 v4, 1.0, v4
	v_rcp_f32_e32 v4, v4
	s_nop 0
	v_mul_f32_e32 v3, v4, v3
	s_nop 1
	v_mov_b32_dpp v4, v3 quad_perm:[1,0,3,2] row_mask:0xf bank_mask:0xf
	s_and_saveexec_b64 s[0:1], vcc
	s_cbranch_execz .LBB0_532
	s_waitcnt lgkmcnt(0)
	v_cvt_pk_bf16_f32 v3, v3, v4
	global_store_dword v[0:1], v3, off offset:2112
.LBB0_532:
	s_or_b64 exec, exec, s[0:1]
	v_lshlrev_b32_e32 v3, 16, v137
	s_waitcnt lgkmcnt(0)
	v_mul_f32_e32 v4, 0xbfb8aa3b, v3
	v_exp_f32_e32 v4, v4
	v_mul_f32_e32 v5, v37, v2
	v_mul_f32_e32 v3, v5, v3
	v_add_f32_e32 v4, 1.0, v4
	v_rcp_f32_e32 v4, v4
	s_nop 0
	v_mul_f32_e32 v3, v4, v3
	s_nop 1
	v_mov_b32_dpp v4, v3 quad_perm:[1,0,3,2] row_mask:0xf bank_mask:0xf
	s_and_saveexec_b64 s[0:1], vcc
	s_cbranch_execz .LBB0_534
	s_waitcnt lgkmcnt(0)
	v_cvt_pk_bf16_f32 v3, v3, v4
	global_store_dword v[0:1], v3, off offset:2176
.LBB0_534:
	s_or_b64 exec, exec, s[0:1]
	v_lshlrev_b32_e32 v3, 16, v136
	s_waitcnt lgkmcnt(0)
	v_mul_f32_e32 v4, 0xbfb8aa3b, v3
	v_exp_f32_e32 v4, v4
	v_mul_f32_e32 v2, v53, v2
	v_mul_f32_e32 v2, v2, v3
	v_add_f32_e32 v4, 1.0, v4
	v_rcp_f32_e32 v4, v4
	s_nop 0
	v_mul_f32_e32 v2, v4, v2
	s_nop 1
	v_mov_b32_dpp v3, v2 quad_perm:[1,0,3,2] row_mask:0xf bank_mask:0xf
	s_and_saveexec_b64 s[0:1], vcc
	s_cbranch_execz .LBB0_536
	s_waitcnt lgkmcnt(0)
	v_cvt_pk_bf16_f32 v2, v2, v3
	global_store_dword v[0:1], v2, off offset:2240
.LBB0_536:
	s_or_b64 exec, exec, s[0:1]
	ds_read2_b32 v[0:1], v68 offset0:10 offset1:138
	s_waitcnt lgkmcnt(1)
	v_lshlrev_b32_e32 v3, 16, v135
	v_mul_f32_e32 v2, 0xbfb8aa3b, v3
	v_exp_f32_e32 v4, v2
	v_lshl_or_b32 v152, v191, 12, v179
	s_waitcnt lgkmcnt(0)
	v_add_f32_e32 v0, v0, v1
	v_fmamk_f32 v0, v0, 0x3b800000, v161
	v_rsq_f32_e32 v2, v0
	v_add_f32_e32 v0, 1.0, v4
	v_rcp_f32_e32 v0, v0
	v_mul_f32_e32 v1, v6, v2
	v_mul_f32_e32 v1, v1, v3
	v_mul_f32_e32 v3, v0, v1
	s_nop 1
	v_mov_b32_dpp v4, v3 quad_perm:[1,0,3,2] row_mask:0xf bank_mask:0xf
	v_lshl_add_u64 v[0:1], v[64:65], 0, v[152:153]
	s_and_saveexec_b64 s[0:1], vcc
	s_cbranch_execz .LBB0_538
	s_waitcnt lgkmcnt(0)
	v_cvt_pk_bf16_f32 v3, v3, v4
	global_store_dword v[0:1], v3, off offset:2048
.LBB0_538:
	s_or_b64 exec, exec, s[0:1]
	v_lshlrev_b32_e32 v3, 16, v134
	s_waitcnt lgkmcnt(0)
	v_mul_f32_e32 v4, 0xbfb8aa3b, v3
	v_exp_f32_e32 v4, v4
	v_mul_f32_e32 v5, v22, v2
	v_mul_f32_e32 v3, v5, v3
	v_add_f32_e32 v4, 1.0, v4
	v_rcp_f32_e32 v4, v4
	s_nop 0
	v_mul_f32_e32 v3, v4, v3
	s_nop 1
	v_mov_b32_dpp v4, v3 quad_perm:[1,0,3,2] row_mask:0xf bank_mask:0xf
	s_and_saveexec_b64 s[0:1], vcc
	s_cbranch_execz .LBB0_540
	s_waitcnt lgkmcnt(0)
	v_cvt_pk_bf16_f32 v3, v3, v4
	global_store_dword v[0:1], v3, off offset:2112
.LBB0_540:
	s_or_b64 exec, exec, s[0:1]
	v_lshlrev_b32_e32 v3, 16, v133
	s_waitcnt lgkmcnt(0)
	v_mul_f32_e32 v4, 0xbfb8aa3b, v3
	v_exp_f32_e32 v4, v4
	v_mul_f32_e32 v5, v38, v2
	v_mul_f32_e32 v3, v5, v3
	v_add_f32_e32 v4, 1.0, v4
	v_rcp_f32_e32 v4, v4
	s_nop 0
	v_mul_f32_e32 v3, v4, v3
	s_nop 1
	v_mov_b32_dpp v4, v3 quad_perm:[1,0,3,2] row_mask:0xf bank_mask:0xf
	s_and_saveexec_b64 s[0:1], vcc
	s_cbranch_execz .LBB0_542
	s_waitcnt lgkmcnt(0)
	v_cvt_pk_bf16_f32 v3, v3, v4
	global_store_dword v[0:1], v3, off offset:2176
.LBB0_542:
	s_or_b64 exec, exec, s[0:1]
	v_lshlrev_b32_e32 v3, 16, v132
	s_waitcnt lgkmcnt(0)
	v_mul_f32_e32 v4, 0xbfb8aa3b, v3
	v_exp_f32_e32 v4, v4
	v_mul_f32_e32 v2, v54, v2
	v_mul_f32_e32 v2, v2, v3
	v_add_f32_e32 v4, 1.0, v4
	v_rcp_f32_e32 v4, v4
	s_nop 0
	v_mul_f32_e32 v2, v4, v2
	s_nop 1
	v_mov_b32_dpp v3, v2 quad_perm:[1,0,3,2] row_mask:0xf bank_mask:0xf
	s_and_saveexec_b64 s[0:1], vcc
	s_cbranch_execz .LBB0_544
	s_waitcnt lgkmcnt(0)
	v_cvt_pk_bf16_f32 v2, v2, v3
	global_store_dword v[0:1], v2, off offset:2240
.LBB0_544:
	s_or_b64 exec, exec, s[0:1]
	ds_read2_b32 v[0:1], v68 offset0:11 offset1:139
	s_waitcnt lgkmcnt(1)
	v_lshlrev_b32_e32 v3, 16, v131
	v_mul_f32_e32 v2, 0xbfb8aa3b, v3
	v_exp_f32_e32 v4, v2
	v_lshl_or_b32 v152, v191, 12, v180
	s_waitcnt lgkmcnt(0)
	v_add_f32_e32 v0, v0, v1
	v_fmamk_f32 v0, v0, 0x3b800000, v161
	v_rsq_f32_e32 v2, v0
	v_add_f32_e32 v0, 1.0, v4
	v_rcp_f32_e32 v0, v0
	v_mul_f32_e32 v1, v7, v2
	v_mul_f32_e32 v1, v1, v3
	v_mul_f32_e32 v3, v0, v1
	s_nop 1
	v_mov_b32_dpp v4, v3 quad_perm:[1,0,3,2] row_mask:0xf bank_mask:0xf
	v_lshl_add_u64 v[0:1], v[64:65], 0, v[152:153]
	s_and_saveexec_b64 s[0:1], vcc
	s_cbranch_execz .LBB0_546
	s_waitcnt lgkmcnt(0)
	v_cvt_pk_bf16_f32 v3, v3, v4
	global_store_dword v[0:1], v3, off offset:2048
.LBB0_546:
	s_or_b64 exec, exec, s[0:1]
	v_lshlrev_b32_e32 v3, 16, v130
	s_waitcnt lgkmcnt(0)
	v_mul_f32_e32 v4, 0xbfb8aa3b, v3
	v_exp_f32_e32 v4, v4
	v_mul_f32_e32 v5, v23, v2
	v_mul_f32_e32 v3, v5, v3
	v_add_f32_e32 v4, 1.0, v4
	v_rcp_f32_e32 v4, v4
	s_nop 0
	v_mul_f32_e32 v3, v4, v3
	s_nop 1
	v_mov_b32_dpp v4, v3 quad_perm:[1,0,3,2] row_mask:0xf bank_mask:0xf
	s_and_saveexec_b64 s[0:1], vcc
	s_cbranch_execz .LBB0_548
	s_waitcnt lgkmcnt(0)
	v_cvt_pk_bf16_f32 v3, v3, v4
	global_store_dword v[0:1], v3, off offset:2112
.LBB0_548:
	s_or_b64 exec, exec, s[0:1]
	v_lshlrev_b32_e32 v3, 16, v129
	s_waitcnt lgkmcnt(0)
	v_mul_f32_e32 v4, 0xbfb8aa3b, v3
	v_exp_f32_e32 v4, v4
	v_mul_f32_e32 v5, v39, v2
	v_mul_f32_e32 v3, v5, v3
	v_add_f32_e32 v4, 1.0, v4
	v_rcp_f32_e32 v4, v4
	s_nop 0
	v_mul_f32_e32 v3, v4, v3
	s_nop 1
	v_mov_b32_dpp v4, v3 quad_perm:[1,0,3,2] row_mask:0xf bank_mask:0xf
	s_and_saveexec_b64 s[0:1], vcc
	s_cbranch_execz .LBB0_550
	s_waitcnt lgkmcnt(0)
	v_cvt_pk_bf16_f32 v3, v3, v4
	global_store_dword v[0:1], v3, off offset:2176
; __device__ __forceinline__ int crow(int r, int hi) { return (r & 3) + 8 * (r >> 2) + 4 * hi; }
; __device__ __forceinline__ unsigned cvtpk(float lo, float hi) { unsigned r; asm volatile("v_cvt_pk_bf16_f32 %0, %1, %2" : "=v"(r) : "v"(lo), "v"(hi)); return r; }
; __device__ __forceinline__ float bf2f(bf16_t v) { return __uint_as_float(((unsigned)v) << 16); }
; __device__ __forceinline__ void ret_block(const bf16_t* __restrict__ proj, const bf16_t* __restrict__ state, bf16_t* __restrict__ mixed, int b, int h, int qb, char* lds) {
;     ...
; #pragma unroll
;     for (int r = 0; r < 16; ++r) { const int orow = crow(r, hi); const float tot = ssx[wq * 32 + orow] + ssx[128 + wq * 32 + orow];
;         const float rs = __builtin_amdgcn_rsqf(tot * (1.0f / 256.0f) + 1e-6f);
; #pragma unroll
;         for (int d0 = 0; d0 < 4; ++d0) { const float g = bf2f(graw[r][d0]);
;             const float v = o[d0][r] * rs * g * __builtin_amdgcn_rcpf(1.0f + __builtin_amdgcn_exp2f(-LOG2E * g)); const float vn = __shfl_xor(v, 1);
;             if ((r32 & 1) == 0) *(unsigned*)(Op + (size_t)orow * LDO + d0 * 32 + r32) = cvtpk(v, vn); } }
.LBB0_550:
	s_or_b64 exec, exec, s[0:1]
	v_lshlrev_b32_e32 v3, 16, v128
	s_waitcnt lgkmcnt(0)
	v_mul_f32_e32 v4, 0xbfb8aa3b, v3
	v_exp_f32_e32 v4, v4
	v_mul_f32_e32 v2, v55, v2
	v_mul_f32_e32 v2, v2, v3
	v_add_f32_e32 v4, 1.0, v4
	v_rcp_f32_e32 v4, v4
	s_nop 0
	v_mul_f32_e32 v2, v4, v2
	s_nop 1
	v_mov_b32_dpp v3, v2 quad_perm:[1,0,3,2] row_mask:0xf bank_mask:0xf
	s_and_saveexec_b64 s[0:1], vcc
	s_cbranch_execz .LBB0_552
	s_waitcnt lgkmcnt(0)
	v_cvt_pk_bf16_f32 v2, v2, v3
	global_store_dword v[0:1], v2, off offset:2240
.LBB0_552:
	s_or_b64 exec, exec, s[0:1]
	ds_read2_b32 v[0:1], v68 offset0:16 offset1:144
	s_waitcnt lgkmcnt(1)
	v_lshlrev_b32_e32 v3, 16, v127
	v_mul_f32_e32 v2, 0xbfb8aa3b, v3
	v_exp_f32_e32 v4, v2
	v_lshl_or_b32 v152, v191, 12, v181
	s_waitcnt lgkmcnt(0)
	v_add_f32_e32 v0, v0, v1
	v_fmamk_f32 v0, v0, 0x3b800000, v161
	v_rsq_f32_e32 v2, v0
	v_add_f32_e32 v0, 1.0, v4
	v_rcp_f32_e32 v0, v0
	v_mul_f32_e32 v1, v8, v2
	v_mul_f32_e32 v1, v1, v3
	v_mul_f32_e32 v3, v0, v1
	s_nop 1
	v_mov_b32_dpp v4, v3 quad_perm:[1,0,3,2] row_mask:0xf bank_mask:0xf
	v_lshl_add_u64 v[0:1], v[64:65], 0, v[152:153]
	s_and_saveexec_b64 s[0:1], vcc
	s_cbranch_execz .LBB0_554
	s_waitcnt lgkmcnt(0)
	v_cvt_pk_bf16_f32 v3, v3, v4
	global_store_dword v[0:1], v3, off offset:2048
.LBB0_554:
	s_or_b64 exec, exec, s[0:1]
	v_lshlrev_b32_e32 v3, 16, v126
	s_waitcnt lgkmcnt(0)
	v_mul_f32_e32 v4, 0xbfb8aa3b, v3
	v_exp_f32_e32 v4, v4
	v_mul_f32_e32 v5, v24, v2
	v_mul_f32_e32 v3, v5, v3
	v_add_f32_e32 v4, 1.0, v4
	v_rcp_f32_e32 v4, v4
	s_nop 0
	v_mul_f32_e32 v3, v4, v3
	s_nop 1
	v_mov_b32_dpp v4, v3 quad_perm:[1,0,3,2] row_mask:0xf bank_mask:0xf
	s_and_saveexec_b64 s[0:1], vcc
	s_cbranch_execz .LBB0_556
	s_waitcnt lgkmcnt(0)
	v_cvt_pk_bf16_f32 v3, v3, v4
	global_store_dword v[0:1], v3, off offset:2112
.LBB0_556:
	s_or_b64 exec, exec, s[0:1]
	v_lshlrev_b32_e32 v3, 16, v125
	s_waitcnt lgkmcnt(0)
	v_mul_f32_e32 v4, 0xbfb8aa3b, v3
	v_exp_f32_e32 v4, v4
	v_mul_f32_e32 v5, v40, v2
	v_mul_f32_e32 v3, v5, v3
	v_add_f32_e32 v4, 1.0, v4
	v_rcp_f32_e32 v4, v4
	s_nop 0
	v_mul_f32_e32 v3, v4, v3
	s_nop 1
	v_mov_b32_dpp v4, v3 quad_perm:[1,0,3,2] row_mask:0xf bank_mask:0xf
	s_and_saveexec_b64 s[0:1], vcc
	s_cbranch_execz .LBB0_558
	s_waitcnt lgkmcnt(0)
	v_cvt_pk_bf16_f32 v3, v3, v4
	global_store_dword v[0:1], v3, off offset:2176
.LBB0_558:
	s_or_b64 exec, exec, s[0:1]
	v_lshlrev_b32_e32 v3, 16, v124
	s_waitcnt lgkmcnt(0)
	v_mul_f32_e32 v4, 0xbfb8aa3b, v3
	v_exp_f32_e32 v4, v4
	v_mul_f32_e32 v2, v56, v2
	v_mul_f32_e32 v2, v2, v3
	v_add_f32_e32 v4, 1.0, v4
	v_rcp_f32_e32 v4, v4
	s_nop 0
	v_mul_f32_e32 v2, v4, v2
	s_nop 1
	v_mov_b32_dpp v3, v2 quad_perm:[1,0,3,2] row_mask:0xf bank_mask:0xf
	s_and_saveexec_b64 s[0:1], vcc
	s_cbranch_execz .LBB0_560
	s_waitcnt lgkmcnt(0)
	v_cvt_pk_bf16_f32 v2, v2, v3
	global_store_dword v[0:1], v2, off offset:2240
.LBB0_560:
	s_or_b64 exec, exec, s[0:1]
	ds_read2_b32 v[0:1], v68 offset0:17 offset1:145
	s_waitcnt lgkmcnt(1)
	v_lshlrev_b32_e32 v3, 16, v123
	v_mul_f32_e32 v2, 0xbfb8aa3b, v3
	v_exp_f32_e32 v4, v2
	v_lshl_or_b32 v152, v191, 12, v182
	s_waitcnt lgkmcnt(0)
	v_add_f32_e32 v0, v0, v1
	v_fmamk_f32 v0, v0, 0x3b800000, v161
	v_rsq_f32_e32 v2, v0
	v_add_f32_e32 v0, 1.0, v4
	v_rcp_f32_e32 v0, v0
	v_mul_f32_e32 v1, v9, v2
	v_mul_f32_e32 v1, v1, v3
	v_mul_f32_e32 v3, v0, v1
	s_nop 1
	v_mov_b32_dpp v4, v3 quad_perm:[1,0,3,2] row_mask:0xf bank_mask:0xf
	v_lshl_add_u64 v[0:1], v[64:65], 0, v[152:153]
	s_and_saveexec_b64 s[0:1], vcc
	s_cbranch_execz .LBB0_562
	s_waitcnt lgkmcnt(0)
	v_cvt_pk_bf16_f32 v3, v3, v4
	global_store_dword v[0:1], v3, off offset:2048
.LBB0_562:
	s_or_b64 exec, exec, s[0:1]
	v_lshlrev_b32_e32 v3, 16, v122
	s_waitcnt lgkmcnt(0)
	v_mul_f32_e32 v4, 0xbfb8aa3b, v3
	v_exp_f32_e32 v4, v4
	v_mul_f32_e32 v5, v25, v2
	v_mul_f32_e32 v3, v5, v3
	v_add_f32_e32 v4, 1.0, v4
	v_rcp_f32_e32 v4, v4
	s_nop 0
	v_mul_f32_e32 v3, v4, v3
	s_nop 1
	v_mov_b32_dpp v4, v3 quad_perm:[1,0,3,2] row_mask:0xf bank_mask:0xf
	s_and_saveexec_b64 s[0:1], vcc
	s_cbranch_execz .LBB0_564
	s_waitcnt lgkmcnt(0)
	v_cvt_pk_bf16_f32 v3, v3, v4
	global_store_dword v[0:1], v3, off offset:2112
.LBB0_564:
	s_or_b64 exec, exec, s[0:1]
	v_lshlrev_b32_e32 v3, 16, v121
	s_waitcnt lgkmcnt(0)
	v_mul_f32_e32 v4, 0xbfb8aa3b, v3
	v_exp_f32_e32 v4, v4
	v_mul_f32_e32 v5, v41, v2
	v_mul_f32_e32 v3, v5, v3
	v_add_f32_e32 v4, 1.0, v4
	v_rcp_f32_e32 v4, v4
	s_nop 0
	v_mul_f32_e32 v3, v4, v3
	s_nop 1
	v_mov_b32_dpp v4, v3 quad_perm:[1,0,3,2] row_mask:0xf bank_mask:0xf
	s_and_saveexec_b64 s[0:1], vcc
	s_cbranch_execz .LBB0_566
	s_waitcnt lgkmcnt(0)
	v_cvt_pk_bf16_f32 v3, v3, v4
	global_store_dword v[0:1], v3, off offset:2176
.LBB0_566:
	s_or_b64 exec, exec, s[0:1]
	v_lshlrev_b32_e32 v3, 16, v120
	s_waitcnt lgkmcnt(0)
	v_mul_f32_e32 v4, 0xbfb8aa3b, v3
	v_exp_f32_e32 v4, v4
	v_mul_f32_e32 v2, v57, v2
	v_mul_f32_e32 v2, v2, v3
	v_add_f32_e32 v4, 1.0, v4
	v_rcp_f32_e32 v4, v4
	s_nop 0
	v_mul_f32_e32 v2, v4, v2
	s_nop 1
	v_mov_b32_dpp v3, v2 quad_perm:[1,0,3,2] row_mask:0xf bank_mask:0xf
	s_and_saveexec_b64 s[0:1], vcc
	s_cbranch_execz .LBB0_568
	s_waitcnt lgkmcnt(0)
	v_cvt_pk_bf16_f32 v2, v2, v3
	global_store_dword v[0:1], v2, off offset:2240
.LBB0_568:
	s_or_b64 exec, exec, s[0:1]
	ds_read2_b32 v[0:1], v68 offset0:18 offset1:146
	s_waitcnt lgkmcnt(1)
	v_lshlrev_b32_e32 v3, 16, v119
	v_mul_f32_e32 v2, 0xbfb8aa3b, v3
	v_exp_f32_e32 v4, v2
	v_lshl_or_b32 v152, v191, 12, v183
	s_waitcnt lgkmcnt(0)
	v_add_f32_e32 v0, v0, v1
	v_fmamk_f32 v0, v0, 0x3b800000, v161
	v_rsq_f32_e32 v2, v0
	v_add_f32_e32 v0, 1.0, v4
	v_rcp_f32_e32 v0, v0
	v_mul_f32_e32 v1, v10, v2
	v_mul_f32_e32 v1, v1, v3
	v_mul_f32_e32 v3, v0, v1
	s_nop 1
	v_mov_b32_dpp v4, v3 quad_perm:[1,0,3,2] row_mask:0xf bank_mask:0xf
	v_lshl_add_u64 v[0:1], v[64:65], 0, v[152:153]
	s_and_saveexec_b64 s[0:1], vcc
	s_cbranch_execz .LBB0_570
	s_waitcnt lgkmcnt(0)
	v_cvt_pk_bf16_f32 v3, v3, v4
	global_store_dword v[0:1], v3, off offset:2048
; __device__ __forceinline__ int crow(int r, int hi) { return (r & 3) + 8 * (r >> 2) + 4 * hi; }
; __device__ __forceinline__ unsigned cvtpk(float lo, float hi) { unsigned r; asm volatile("v_cvt_pk_bf16_f32 %0, %1, %2" : "=v"(r) : "v"(lo), "v"(hi)); return r; }
; __device__ __forceinline__ float bf2f(bf16_t v) { return __uint_as_float(((unsigned)v) << 16); }
; __device__ __forceinline__ void ret_block(const bf16_t* __restrict__ proj, const bf16_t* __restrict__ state, bf16_t* __restrict__ mixed, int b, int h, int qb, char* lds) {
;     ...
; #pragma unroll
;     for (int r = 0; r < 16; ++r) { const int orow = crow(r, hi); const float tot = ssx[wq * 32 + orow] + ssx[128 + wq * 32 + orow];
;         const float rs = __builtin_amdgcn_rsqf(tot * (1.0f / 256.0f) + 1e-6f);
; #pragma unroll
;         for (int d0 = 0; d0 < 4; ++d0) { const float g = bf2f(graw[r][d0]);
;             const float v = o[d0][r] * rs * g * __builtin_amdgcn_rcpf(1.0f + __builtin_amdgcn_exp2f(-LOG2E * g)); const float vn = __shfl_xor(v, 1);
;             if ((r32 & 1) == 0) *(unsigned*)(Op + (size_t)orow * LDO + d0 * 32 + r32) = cvtpk(v, vn); } }
.LBB0_570:
	s_or_b64 exec, exec, s[0:1]
	v_lshlrev_b32_e32 v3, 16, v118
	s_waitcnt lgkmcnt(0)
	v_mul_f32_e32 v4, 0xbfb8aa3b, v3
	v_exp_f32_e32 v4, v4
	v_mul_f32_e32 v5, v26, v2
	v_mul_f32_e32 v3, v5, v3
	v_add_f32_e32 v4, 1.0, v4
	v_rcp_f32_e32 v4, v4
	s_nop 0
	v_mul_f32_e32 v3, v4, v3
	s_nop 1
	v_mov_b32_dpp v4, v3 quad_perm:[1,0,3,2] row_mask:0xf bank_mask:0xf
	s_and_saveexec_b64 s[0:1], vcc
	s_cbranch_execz .LBB0_572
	s_waitcnt lgkmcnt(0)
	v_cvt_pk_bf16_f32 v3, v3, v4
	global_store_dword v[0:1], v3, off offset:2112
.LBB0_572:
	s_or_b64 exec, exec, s[0:1]
	v_lshlrev_b32_e32 v3, 16, v117
	s_waitcnt lgkmcnt(0)
	v_mul_f32_e32 v4, 0xbfb8aa3b, v3
	v_exp_f32_e32 v4, v4
	v_mul_f32_e32 v5, v42, v2
	v_mul_f32_e32 v3, v5, v3
	v_add_f32_e32 v4, 1.0, v4
	v_rcp_f32_e32 v4, v4
	s_nop 0
	v_mul_f32_e32 v3, v4, v3
	s_nop 1
	v_mov_b32_dpp v4, v3 quad_perm:[1,0,3,2] row_mask:0xf bank_mask:0xf
	s_and_saveexec_b64 s[0:1], vcc
	s_cbranch_execz .LBB0_574
	s_waitcnt lgkmcnt(0)
	v_cvt_pk_bf16_f32 v3, v3, v4
	global_store_dword v[0:1], v3, off offset:2176
.LBB0_574:
	s_or_b64 exec, exec, s[0:1]
	v_lshlrev_b32_e32 v3, 16, v116
	s_waitcnt lgkmcnt(0)
	v_mul_f32_e32 v4, 0xbfb8aa3b, v3
	v_exp_f32_e32 v4, v4
	v_mul_f32_e32 v2, v58, v2
	v_mul_f32_e32 v2, v2, v3
	v_add_f32_e32 v4, 1.0, v4
	v_rcp_f32_e32 v4, v4
	s_nop 0
	v_mul_f32_e32 v2, v4, v2
	s_nop 1
	v_mov_b32_dpp v3, v2 quad_perm:[1,0,3,2] row_mask:0xf bank_mask:0xf
	s_and_saveexec_b64 s[0:1], vcc
	s_cbranch_execz .LBB0_576
	s_waitcnt lgkmcnt(0)
	v_cvt_pk_bf16_f32 v2, v2, v3
	global_store_dword v[0:1], v2, off offset:2240
.LBB0_576:
	s_or_b64 exec, exec, s[0:1]
	ds_read2_b32 v[0:1], v68 offset0:19 offset1:147
	s_waitcnt lgkmcnt(1)
	v_lshlrev_b32_e32 v3, 16, v115
	v_mul_f32_e32 v2, 0xbfb8aa3b, v3
	v_exp_f32_e32 v4, v2
	v_lshl_or_b32 v152, v191, 12, v186
	s_waitcnt lgkmcnt(0)
	v_add_f32_e32 v0, v0, v1
	v_fmamk_f32 v0, v0, 0x3b800000, v161
	v_rsq_f32_e32 v2, v0
	v_add_f32_e32 v0, 1.0, v4
	v_rcp_f32_e32 v0, v0
	v_mul_f32_e32 v1, v11, v2
	v_mul_f32_e32 v1, v1, v3
	v_mul_f32_e32 v3, v0, v1
	s_nop 1
	v_mov_b32_dpp v4, v3 quad_perm:[1,0,3,2] row_mask:0xf bank_mask:0xf
	v_lshl_add_u64 v[0:1], v[64:65], 0, v[152:153]
	s_and_saveexec_b64 s[0:1], vcc
	s_cbranch_execz .LBB0_578
	s_waitcnt lgkmcnt(0)
	v_cvt_pk_bf16_f32 v3, v3, v4
	global_store_dword v[0:1], v3, off offset:2048
.LBB0_578:
	s_or_b64 exec, exec, s[0:1]
	v_lshlrev_b32_e32 v3, 16, v114
	s_waitcnt lgkmcnt(0)
	v_mul_f32_e32 v4, 0xbfb8aa3b, v3
	v_exp_f32_e32 v4, v4
	v_mul_f32_e32 v5, v27, v2
	v_mul_f32_e32 v3, v5, v3
	v_add_f32_e32 v4, 1.0, v4
	v_rcp_f32_e32 v4, v4
	s_nop 0
	v_mul_f32_e32 v3, v4, v3
	s_nop 1
	v_mov_b32_dpp v4, v3 quad_perm:[1,0,3,2] row_mask:0xf bank_mask:0xf
	s_and_saveexec_b64 s[0:1], vcc
	s_cbranch_execz .LBB0_580
	s_waitcnt lgkmcnt(0)
	v_cvt_pk_bf16_f32 v3, v3, v4
	global_store_dword v[0:1], v3, off offset:2112
.LBB0_580:
	s_or_b64 exec, exec, s[0:1]
	v_lshlrev_b32_e32 v3, 16, v113
	s_waitcnt lgkmcnt(0)
	v_mul_f32_e32 v4, 0xbfb8aa3b, v3
	v_exp_f32_e32 v4, v4
	v_mul_f32_e32 v5, v43, v2
	v_mul_f32_e32 v3, v5, v3
	v_add_f32_e32 v4, 1.0, v4
	v_rcp_f32_e32 v4, v4
	s_nop 0
	v_mul_f32_e32 v3, v4, v3
	s_nop 1
	v_mov_b32_dpp v4, v3 quad_perm:[1,0,3,2] row_mask:0xf bank_mask:0xf
	s_and_saveexec_b64 s[0:1], vcc
	s_cbranch_execz .LBB0_582
	s_waitcnt lgkmcnt(0)
	v_cvt_pk_bf16_f32 v3, v3, v4
	global_store_dword v[0:1], v3, off offset:2176
.LBB0_582:
	s_or_b64 exec, exec, s[0:1]
	v_lshlrev_b32_e32 v3, 16, v112
	s_waitcnt lgkmcnt(0)
	v_mul_f32_e32 v4, 0xbfb8aa3b, v3
	v_exp_f32_e32 v4, v4
	v_mul_f32_e32 v2, v59, v2
	v_mul_f32_e32 v2, v2, v3
	v_add_f32_e32 v4, 1.0, v4
	v_rcp_f32_e32 v4, v4
	s_nop 0
	v_mul_f32_e32 v2, v4, v2
	s_nop 1
	v_mov_b32_dpp v3, v2 quad_perm:[1,0,3,2] row_mask:0xf bank_mask:0xf
	s_and_saveexec_b64 s[0:1], vcc
	s_cbranch_execz .LBB0_584
	s_waitcnt lgkmcnt(0)
	v_cvt_pk_bf16_f32 v2, v2, v3
	global_store_dword v[0:1], v2, off offset:2240
.LBB0_584:
	s_or_b64 exec, exec, s[0:1]
	ds_read2_b32 v[0:1], v68 offset0:24 offset1:152
	s_waitcnt lgkmcnt(1)
	v_lshlrev_b32_e32 v3, 16, v111
	v_mul_f32_e32 v2, 0xbfb8aa3b, v3
	v_exp_f32_e32 v4, v2
	v_lshl_or_b32 v152, v191, 12, v187
	s_waitcnt lgkmcnt(0)
	v_add_f32_e32 v0, v0, v1
	v_fmamk_f32 v0, v0, 0x3b800000, v161
	v_rsq_f32_e32 v2, v0
	v_add_f32_e32 v0, 1.0, v4
	v_rcp_f32_e32 v0, v0
	v_mul_f32_e32 v1, v12, v2
	v_mul_f32_e32 v1, v1, v3
	v_mul_f32_e32 v3, v0, v1
	s_nop 1
	v_mov_b32_dpp v4, v3 quad_perm:[1,0,3,2] row_mask:0xf bank_mask:0xf
	v_lshl_add_u64 v[0:1], v[64:65], 0, v[152:153]
	s_and_saveexec_b64 s[0:1], vcc
	s_cbranch_execz .LBB0_586
	s_waitcnt lgkmcnt(0)
	v_cvt_pk_bf16_f32 v3, v3, v4
	global_store_dword v[0:1], v3, off offset:2048
.LBB0_586:
	s_or_b64 exec, exec, s[0:1]
	v_lshlrev_b32_e32 v3, 16, v110
	s_waitcnt lgkmcnt(0)
	v_mul_f32_e32 v4, 0xbfb8aa3b, v3
	v_exp_f32_e32 v4, v4
	v_mul_f32_e32 v5, v28, v2
	v_mul_f32_e32 v3, v5, v3
	v_add_f32_e32 v4, 1.0, v4
	v_rcp_f32_e32 v4, v4
	s_nop 0
	v_mul_f32_e32 v3, v4, v3
	s_nop 1
	v_mov_b32_dpp v4, v3 quad_perm:[1,0,3,2] row_mask:0xf bank_mask:0xf
	s_and_saveexec_b64 s[0:1], vcc
	s_cbranch_execz .LBB0_588
	s_waitcnt lgkmcnt(0)
	v_cvt_pk_bf16_f32 v3, v3, v4
	global_store_dword v[0:1], v3, off offset:2112
.LBB0_588:
	s_or_b64 exec, exec, s[0:1]
	v_lshlrev_b32_e32 v3, 16, v109
	s_waitcnt lgkmcnt(0)
	v_mul_f32_e32 v4, 0xbfb8aa3b, v3
	v_exp_f32_e32 v4, v4
	v_mul_f32_e32 v5, v44, v2
	v_mul_f32_e32 v3, v5, v3
	v_add_f32_e32 v4, 1.0, v4
	v_rcp_f32_e32 v4, v4
	s_nop 0
	v_mul_f32_e32 v3, v4, v3
	s_nop 1
	v_mov_b32_dpp v4, v3 quad_perm:[1,0,3,2] row_mask:0xf bank_mask:0xf
	s_and_saveexec_b64 s[0:1], vcc
	s_cbranch_execz .LBB0_590
	s_waitcnt lgkmcnt(0)
	v_cvt_pk_bf16_f32 v3, v3, v4
	global_store_dword v[0:1], v3, off offset:2176
; __device__ __forceinline__ int crow(int r, int hi) { return (r & 3) + 8 * (r >> 2) + 4 * hi; }
; __device__ __forceinline__ unsigned cvtpk(float lo, float hi) { unsigned r; asm volatile("v_cvt_pk_bf16_f32 %0, %1, %2" : "=v"(r) : "v"(lo), "v"(hi)); return r; }
; __device__ __forceinline__ float bf2f(bf16_t v) { return __uint_as_float(((unsigned)v) << 16); }
; __device__ __forceinline__ void ret_block(const bf16_t* __restrict__ proj, const bf16_t* __restrict__ state, bf16_t* __restrict__ mixed, int b, int h, int qb, char* lds) {
;     ...
; #pragma unroll
;     for (int r = 0; r < 16; ++r) { const int orow = crow(r, hi); const float tot = ssx[wq * 32 + orow] + ssx[128 + wq * 32 + orow];
;         const float rs = __builtin_amdgcn_rsqf(tot * (1.0f / 256.0f) + 1e-6f);
; #pragma unroll
;         for (int d0 = 0; d0 < 4; ++d0) { const float g = bf2f(graw[r][d0]);
;             const float v = o[d0][r] * rs * g * __builtin_amdgcn_rcpf(1.0f + __builtin_amdgcn_exp2f(-LOG2E * g)); const float vn = __shfl_xor(v, 1);
;             if ((r32 & 1) == 0) *(unsigned*)(Op + (size_t)orow * LDO + d0 * 32 + r32) = cvtpk(v, vn); } }
.LBB0_590:
	s_or_b64 exec, exec, s[0:1]
	v_lshlrev_b32_e32 v3, 16, v108
	s_waitcnt lgkmcnt(0)
	v_mul_f32_e32 v4, 0xbfb8aa3b, v3
	v_exp_f32_e32 v4, v4
	v_mul_f32_e32 v2, v60, v2
	v_mul_f32_e32 v2, v2, v3
	v_add_f32_e32 v4, 1.0, v4
	v_rcp_f32_e32 v4, v4
	s_nop 0
	v_mul_f32_e32 v2, v4, v2
	s_nop 1
	v_mov_b32_dpp v3, v2 quad_perm:[1,0,3,2] row_mask:0xf bank_mask:0xf
	s_and_saveexec_b64 s[0:1], vcc
	s_cbranch_execz .LBB0_592
	s_waitcnt lgkmcnt(0)
	v_cvt_pk_bf16_f32 v2, v2, v3
	global_store_dword v[0:1], v2, off offset:2240
.LBB0_592:
	s_or_b64 exec, exec, s[0:1]
	ds_read2_b32 v[0:1], v68 offset0:25 offset1:153
	s_waitcnt lgkmcnt(1)
	v_lshlrev_b32_e32 v3, 16, v107
	v_mul_f32_e32 v2, 0xbfb8aa3b, v3
	v_exp_f32_e32 v4, v2
	v_lshl_or_b32 v152, v191, 12, v188
	s_waitcnt lgkmcnt(0)
	v_add_f32_e32 v0, v0, v1
	v_fmamk_f32 v0, v0, 0x3b800000, v161
	v_rsq_f32_e32 v2, v0
	v_add_f32_e32 v0, 1.0, v4
	v_rcp_f32_e32 v0, v0
	v_mul_f32_e32 v1, v13, v2
	v_mul_f32_e32 v1, v1, v3
	v_mul_f32_e32 v3, v0, v1
	s_nop 1
	v_mov_b32_dpp v4, v3 quad_perm:[1,0,3,2] row_mask:0xf bank_mask:0xf
	v_lshl_add_u64 v[0:1], v[64:65], 0, v[152:153]
	s_and_saveexec_b64 s[0:1], vcc
	s_cbranch_execz .LBB0_594
	s_waitcnt lgkmcnt(0)
	v_cvt_pk_bf16_f32 v3, v3, v4
	global_store_dword v[0:1], v3, off offset:2048
.LBB0_594:
	s_or_b64 exec, exec, s[0:1]
	v_lshlrev_b32_e32 v3, 16, v106
	s_waitcnt lgkmcnt(0)
	v_mul_f32_e32 v4, 0xbfb8aa3b, v3
	v_exp_f32_e32 v4, v4
	v_mul_f32_e32 v5, v29, v2
	v_mul_f32_e32 v3, v5, v3
	v_add_f32_e32 v4, 1.0, v4
	v_rcp_f32_e32 v4, v4
	s_nop 0
	v_mul_f32_e32 v3, v4, v3
	s_nop 1
	v_mov_b32_dpp v4, v3 quad_perm:[1,0,3,2] row_mask:0xf bank_mask:0xf
	s_and_saveexec_b64 s[0:1], vcc
	s_cbranch_execz .LBB0_596
	s_waitcnt lgkmcnt(0)
	v_cvt_pk_bf16_f32 v3, v3, v4
	global_store_dword v[0:1], v3, off offset:2112
.LBB0_596:
	s_or_b64 exec, exec, s[0:1]
	v_lshlrev_b32_e32 v3, 16, v105
	s_waitcnt lgkmcnt(0)
	v_mul_f32_e32 v4, 0xbfb8aa3b, v3
	v_exp_f32_e32 v4, v4
	v_mul_f32_e32 v5, v45, v2
	v_mul_f32_e32 v3, v5, v3
	v_add_f32_e32 v4, 1.0, v4
	v_rcp_f32_e32 v4, v4
	s_nop 0
	v_mul_f32_e32 v3, v4, v3
	s_nop 1
	v_mov_b32_dpp v4, v3 quad_perm:[1,0,3,2] row_mask:0xf bank_mask:0xf
	s_and_saveexec_b64 s[0:1], vcc
	s_cbranch_execz .LBB0_598
	s_waitcnt lgkmcnt(0)
	v_cvt_pk_bf16_f32 v3, v3, v4
	global_store_dword v[0:1], v3, off offset:2176
.LBB0_598:
	s_or_b64 exec, exec, s[0:1]
	v_lshlrev_b32_e32 v3, 16, v104
	s_waitcnt lgkmcnt(0)
	v_mul_f32_e32 v4, 0xbfb8aa3b, v3
	v_exp_f32_e32 v4, v4
	v_mul_f32_e32 v2, v61, v2
	v_mul_f32_e32 v2, v2, v3
	v_add_f32_e32 v4, 1.0, v4
	v_rcp_f32_e32 v4, v4
	s_nop 0
	v_mul_f32_e32 v2, v4, v2
	s_nop 1
	v_mov_b32_dpp v3, v2 quad_perm:[1,0,3,2] row_mask:0xf bank_mask:0xf
	s_and_saveexec_b64 s[0:1], vcc
	s_cbranch_execz .LBB0_600
	s_waitcnt lgkmcnt(0)
	v_cvt_pk_bf16_f32 v2, v2, v3
	global_store_dword v[0:1], v2, off offset:2240
.LBB0_600:
	s_or_b64 exec, exec, s[0:1]
	ds_read2_b32 v[0:1], v68 offset0:26 offset1:154
	s_waitcnt lgkmcnt(1)
	v_lshlrev_b32_e32 v3, 16, v103
	v_mul_f32_e32 v2, 0xbfb8aa3b, v3
	v_exp_f32_e32 v4, v2
	v_lshl_or_b32 v152, v191, 12, v189
	s_waitcnt lgkmcnt(0)
	v_add_f32_e32 v0, v0, v1
	v_fmamk_f32 v0, v0, 0x3b800000, v161
	v_rsq_f32_e32 v2, v0
	v_add_f32_e32 v0, 1.0, v4
	v_rcp_f32_e32 v0, v0
	v_mul_f32_e32 v1, v14, v2
	v_mul_f32_e32 v1, v1, v3
	v_mul_f32_e32 v3, v0, v1
	s_nop 1
	v_mov_b32_dpp v4, v3 quad_perm:[1,0,3,2] row_mask:0xf bank_mask:0xf
	v_lshl_add_u64 v[0:1], v[64:65], 0, v[152:153]
	s_and_saveexec_b64 s[0:1], vcc
	s_cbranch_execz .LBB0_602
	s_waitcnt lgkmcnt(0)
	v_cvt_pk_bf16_f32 v3, v3, v4
	global_store_dword v[0:1], v3, off offset:2048
; __device__ __forceinline__ int crow(int r, int hi) { return (r & 3) + 8 * (r >> 2) + 4 * hi; }
; __device__ __forceinline__ unsigned cvtpk(float lo, float hi) { unsigned r; asm volatile("v_cvt_pk_bf16_f32 %0, %1, %2" : "=v"(r) : "v"(lo), "v"(hi)); return r; }
; __device__ __forceinline__ float bf2f(bf16_t v) { return __uint_as_float(((unsigned)v) << 16); }
; __device__ __forceinline__ void ret_block(const bf16_t* __restrict__ proj, const bf16_t* __restrict__ state, bf16_t* __restrict__ mixed, int b, int h, int qb, char* lds) {
;     ...
; #pragma unroll
;     for (int r = 0; r < 16; ++r) { const int orow = crow(r, hi); const float tot = ssx[wq * 32 + orow] + ssx[128 + wq * 32 + orow];
;         const float rs = __builtin_amdgcn_rsqf(tot * (1.0f / 256.0f) + 1e-6f);
; #pragma unroll
;         for (int d0 = 0; d0 < 4; ++d0) { const float g = bf2f(graw[r][d0]);
;             const float v = o[d0][r] * rs * g * __builtin_amdgcn_rcpf(1.0f + __builtin_amdgcn_exp2f(-LOG2E * g)); const float vn = __shfl_xor(v, 1);
;             if ((r32 & 1) == 0) *(unsigned*)(Op + (size_t)orow * LDO + d0 * 32 + r32) = cvtpk(v, vn); } }
.LBB0_602:
	s_or_b64 exec, exec, s[0:1]
	v_lshlrev_b32_e32 v3, 16, v102
	s_waitcnt lgkmcnt(0)
	v_mul_f32_e32 v4, 0xbfb8aa3b, v3
	v_exp_f32_e32 v4, v4
	v_mul_f32_e32 v5, v30, v2
	v_mul_f32_e32 v3, v5, v3
	v_add_f32_e32 v4, 1.0, v4
	v_rcp_f32_e32 v4, v4
	s_nop 0
	v_mul_f32_e32 v3, v4, v3
	s_nop 1
	v_mov_b32_dpp v4, v3 quad_perm:[1,0,3,2] row_mask:0xf bank_mask:0xf
	s_and_saveexec_b64 s[0:1], vcc
	s_cbranch_execz .LBB0_604
	s_waitcnt lgkmcnt(0)
	v_cvt_pk_bf16_f32 v3, v3, v4
	global_store_dword v[0:1], v3, off offset:2112
.LBB0_604:
	s_or_b64 exec, exec, s[0:1]
	v_lshlrev_b32_e32 v3, 16, v101
	s_waitcnt lgkmcnt(0)
	v_mul_f32_e32 v4, 0xbfb8aa3b, v3
	v_exp_f32_e32 v4, v4
	v_mul_f32_e32 v5, v46, v2
	v_mul_f32_e32 v3, v5, v3
	v_add_f32_e32 v4, 1.0, v4
	v_rcp_f32_e32 v4, v4
	s_nop 0
	v_mul_f32_e32 v3, v4, v3
	s_nop 1
	v_mov_b32_dpp v4, v3 quad_perm:[1,0,3,2] row_mask:0xf bank_mask:0xf
	s_and_saveexec_b64 s[0:1], vcc
	s_cbranch_execz .LBB0_606
	s_waitcnt lgkmcnt(0)
	v_cvt_pk_bf16_f32 v3, v3, v4
	global_store_dword v[0:1], v3, off offset:2176
.LBB0_606:
	s_or_b64 exec, exec, s[0:1]
	v_lshlrev_b32_e32 v3, 16, v100
	s_waitcnt lgkmcnt(0)
	v_mul_f32_e32 v4, 0xbfb8aa3b, v3
	v_exp_f32_e32 v4, v4
	v_mul_f32_e32 v2, v62, v2
	v_mul_f32_e32 v2, v2, v3
	v_add_f32_e32 v4, 1.0, v4
	v_rcp_f32_e32 v4, v4
	s_nop 0
	v_mul_f32_e32 v2, v4, v2
	s_nop 1
	v_mov_b32_dpp v3, v2 quad_perm:[1,0,3,2] row_mask:0xf bank_mask:0xf
	s_and_saveexec_b64 s[0:1], vcc
	s_cbranch_execz .LBB0_608
	s_waitcnt lgkmcnt(0)
	v_cvt_pk_bf16_f32 v2, v2, v3
	global_store_dword v[0:1], v2, off offset:2240
.LBB0_608:
	s_or_b64 exec, exec, s[0:1]
	ds_read2_b32 v[0:1], v68 offset0:27 offset1:155
	s_waitcnt lgkmcnt(1)
	v_lshlrev_b32_e32 v3, 16, v99
	v_mul_f32_e32 v2, 0xbfb8aa3b, v3
	v_exp_f32_e32 v4, v2
	v_lshl_or_b32 v152, v191, 12, v190
	s_waitcnt lgkmcnt(0)
	v_add_f32_e32 v0, v0, v1
	v_fmamk_f32 v0, v0, 0x3b800000, v161
	v_rsq_f32_e32 v2, v0
	v_add_f32_e32 v0, 1.0, v4
	v_rcp_f32_e32 v0, v0
	v_mul_f32_e32 v1, v15, v2
	v_mul_f32_e32 v1, v1, v3
	v_mul_f32_e32 v3, v0, v1
	s_nop 1
	v_mov_b32_dpp v4, v3 quad_perm:[1,0,3,2] row_mask:0xf bank_mask:0xf
	v_lshl_add_u64 v[0:1], v[64:65], 0, v[152:153]
	s_and_saveexec_b64 s[0:1], vcc
	s_cbranch_execz .LBB0_610
	s_waitcnt lgkmcnt(0)
	v_cvt_pk_bf16_f32 v3, v3, v4
	global_store_dword v[0:1], v3, off offset:2048
.LBB0_610:
	s_or_b64 exec, exec, s[0:1]
	v_lshlrev_b32_e32 v3, 16, v98
	s_waitcnt lgkmcnt(0)
	v_mul_f32_e32 v4, 0xbfb8aa3b, v3
	v_exp_f32_e32 v4, v4
	v_mul_f32_e32 v5, v31, v2
	v_mul_f32_e32 v3, v5, v3
	v_add_f32_e32 v4, 1.0, v4
	v_rcp_f32_e32 v4, v4
	s_nop 0
	v_mul_f32_e32 v3, v4, v3
	s_nop 1
	v_mov_b32_dpp v4, v3 quad_perm:[1,0,3,2] row_mask:0xf bank_mask:0xf
	s_and_saveexec_b64 s[0:1], vcc
	s_cbranch_execz .LBB0_612
	s_waitcnt lgkmcnt(0)
	v_cvt_pk_bf16_f32 v3, v3, v4
	global_store_dword v[0:1], v3, off offset:2112
.LBB0_612:
	s_or_b64 exec, exec, s[0:1]
	v_lshlrev_b32_e32 v3, 16, v97
	s_waitcnt lgkmcnt(0)
	v_mul_f32_e32 v4, 0xbfb8aa3b, v3
	v_exp_f32_e32 v4, v4
	v_mul_f32_e32 v5, v47, v2
	v_mul_f32_e32 v3, v5, v3
	v_add_f32_e32 v4, 1.0, v4
	v_rcp_f32_e32 v4, v4
	s_nop 0
	v_mul_f32_e32 v3, v4, v3
	s_nop 1
	v_mov_b32_dpp v4, v3 quad_perm:[1,0,3,2] row_mask:0xf bank_mask:0xf
	s_and_saveexec_b64 s[0:1], vcc
	s_cbranch_execz .LBB0_614
	s_waitcnt lgkmcnt(0)
	v_cvt_pk_bf16_f32 v3, v3, v4
	global_store_dword v[0:1], v3, off offset:2176
.LBB0_614:
	s_or_b64 exec, exec, s[0:1]
	v_lshlrev_b32_e32 v3, 16, v96
	s_waitcnt lgkmcnt(0)
	v_mul_f32_e32 v4, 0xbfb8aa3b, v3
	v_exp_f32_e32 v4, v4
	v_mul_f32_e32 v2, v63, v2
	v_mul_f32_e32 v2, v2, v3
	v_add_f32_e32 v4, 1.0, v4
	v_rcp_f32_e32 v4, v4
	s_nop 0
	v_mul_f32_e32 v2, v4, v2
	s_nop 1
	v_mov_b32_dpp v3, v2 quad_perm:[1,0,3,2] row_mask:0xf bank_mask:0xf
	s_and_saveexec_b64 s[0:1], vcc
	s_cbranch_execz .LBB0_474
	s_waitcnt lgkmcnt(0)
	v_cvt_pk_bf16_f32 v2, v2, v3
	global_store_dword v[0:1], v2, off offset:2240
	s_branch .LBB0_474
